# attention: conflict-free K swizzle, no setprio, shared rare paths, smaller code
# speedup vs baseline: 1.3908x; 1.0000x over previous
; __device__ __forceinline__ void attn_item(const bf16_t* __restrict__ Qb, const bf16_t* __restrict__ Kn, const bf16_t* __restrict__ Kr, const bf16_t* __restrict__ Vh,
;                                           const float* __restrict__ csq, bf16_t* __restrict__ Ob, int seq, char* lds) {
;   int tid_ = threadIdx.x; asm volatile("" : "+v"(tid_));
;   const int tid = tid_, wid = tid >> 6, lane = tid & 63, r32 = lane & 31, hi = lane >> 5;
;   bf16_t* V_lds = (bf16_t*)lds; bf16_t* K_lds = (bf16_t*)(lds + 3 * SLOT);
;   float* ws = (float*)(lds + 6 * SLOT) + wid * 64; float* li_l = ws; float* al_l = ws + 32;
;   float mhat = 0.f, l_reg = 0; f32x16 o[2] = {}; bf16x8 qr[6]; f32x16 negm = f32x16{};
;   const bf16_t* Qw = Qb + (long)(wid * QBLK + r32) * 1792 + hi * 8;
; #pragma unroll
;   for (int d0 = 0; d0 < 6; ++d0) qr[d0] = *reinterpret_cast<const bf16x8*>(Qw + d0 * 16);
;   { const float* cp = csq + (long)(wid * QBLK + r32) * 32 + hi * 8;
;     const f32x4 c0 = *(const f32x4*)cp, c1 = *(const f32x4*)(cp + 4), s0 = *(const f32x4*)(cp + 16), s1 = *(const f32x4*)(cp + 20);
;     float cc[8] = {c0[0], c0[1], c0[2], c0[3], c1[0], c1[1], c1[2], c1[3]}, ss[8] = {s0[0], s0[1], s0[2], s0[3], s1[0], s1[1], s1[2], s1[3]};
;     bf16x8 n4, n5;
; #pragma unroll
;     for (int e = 0; e < 8; ++e) { const float x1 = bf2f((unsigned short)qr[4][e]), x2 = bf2f((unsigned short)qr[5][e]);
;       n4[e] = (short)f2bf(x1 * cc[e] - x2 * ss[e]); n5[e] = (short)f2bf(x1 * ss[e] + x2 * cc[e]); }
;     qr[4] = n4; qr[5] = n5; }
;   const int sr = tid >> 3, sc = (tid & 7) * 8, vst0 = v_st(sr, sc);
;   const int rr_ = (tid & 255) >> 2, rc_ = (tid & 3) * 8;
;   const int vb0 = (int)(uintptr_t)V_lds + v_rd_base(lane);
;   struct { bf16x8 vs, kn, kr; } sr_[1];
; __global__ void __launch_bounds__(512, 2) mega(Args a_unused) {
;     ...
;             if constexpr (PHMASK & 512) for (int rep = 0; rep <= DUP_ATT; ++rep) for (int it = C.vcu; it < NB * NH * (SEQ / 256); it += C.G) { const int bh = it >> 5, qb = it & 31; const int b = bh >> 3, hh = bh & 7;
;                 const bf16_t* qkvb = Hb + (size_t)b * SEQ * NQKV;
;                 att::attn_item(qkvb + (size_t)(qb * 256) * NQKV + hh * 96, qkvb + 768 + hh * 128, KPE + (size_t)b * SEQ * 32, qkvb + 768 + hh * 128 + 64,
.LBB0_666:
	s_mov_b64 s[8:9], s[84:85]
	s_load_dword s0, s[8:9], 0x120
	s_add_i32 s24, s63, 5
	s_waitcnt lgkmcnt(0)
	s_cmp_lt_i32 s24, s0
	s_cbranch_scc1 .LBB0_707
	s_load_dword s0, s[8:9], 0x124
	s_waitcnt lgkmcnt(0)
	s_cmp_ge_i32 s24, s0
	s_cbranch_scc1 .LBB0_707
	v_readlane_b32 s0, v255, 13
	v_readlane_b32 s1, v255, 14
	v_mov_b32_e32 v1, v180
	s_andn2_b64 vcc, exec, s[0:1]
	s_cbranch_vccnz .LBB0_707
	s_load_dwordx4 s[12:15], s[8:9], 0x110
	v_readlane_b32 s28, v255, 49
	v_and_b32_e32 v1, 63, v180
	v_lshrrev_b32_e32 v177, 6, v180
	s_nop 0
	v_readfirstlane_b32 s29, v177
	v_and_b32_e32 v178, 31, v1
	v_lshrrev_b32_e32 v179, 5, v1
	v_and_b32_e32 v213, 15, v178
	v_lshlrev_b32_e32 v214, 8, v178
	v_add_u32_e32 v214, 65536, v214
	v_or_b32_e32 v215, 0, v179
	v_xor_b32_e32 v215, v215, v213
	v_lshl_add_u32 v140, v215, 4, v214
	v_or_b32_e32 v215, 2, v179
	v_xor_b32_e32 v215, v215, v213
	v_lshl_add_u32 v141, v215, 4, v214
	v_or_b32_e32 v215, 4, v179
	v_xor_b32_e32 v215, v215, v213
	v_lshl_add_u32 v142, v215, 4, v214
	v_or_b32_e32 v215, 6, v179
	v_xor_b32_e32 v215, v215, v213
	v_lshl_add_u32 v143, v215, 4, v214
	v_or_b32_e32 v215, 8, v179
	v_xor_b32_e32 v215, v215, v213
	v_lshl_add_u32 v144, v215, 4, v214
	v_or_b32_e32 v215, 10, v179
	v_xor_b32_e32 v215, v215, v213
	v_lshl_add_u32 v145, v215, 4, v214
	v_and_b32_e32 v213, 3, v1
	v_lshlrev_b32_e32 v213, 3, v213
	v_bfe_u32 v214, v1, 2, 2
	v_lshl_or_b32 v213, v214, 6, v213
	v_bfe_u32 v214, v1, 4, 1
	v_lshl_or_b32 v213, v214, 5, v213
	v_lshl_or_b32 v150, v179, 8, v213
	s_lshl_b32 s0, s29, 8
	s_add_i32 s0, s0, 131072
	v_lshl_add_u32 v175, v178, 2, s0
	v_lshl_add_u32 v176, v179, 4, s0
	s_lshl_b32 s6, s29, 11
	s_mov_b32 s7, s6
	s_add_i32 s6, s6, 65536
	v_and_b32_e32 v213, 15, v1
	v_lshrrev_b32_e32 v214, 4, v1
	s_and_b32 s0, s29, 1
	s_lshl_b32 s0, s0, 3
	v_add_u32_e32 v214, s0, v214
	v_add_u32_e32 v216, 0, v214
	v_xor_b32_e32 v216, v213, v216
	v_cmp_gt_u32_e64 s[20:21], 12, v216
	v_add_u32_e32 v216, 4, v214
	v_xor_b32_e32 v216, v213, v216
	v_cmp_gt_u32_e64 s[22:23], 12, v216
	s_movk_i32 s25, 0x7fff
	s_waitcnt lgkmcnt(0)
	s_mov_b32 s9, 0
.Lat_item:
	s_lshr_b32 s0, s28, 5
	s_and_b32 s1, s28, 31
	s_lshr_b32 s2, s0, 3
	s_and_b32 s0, s0, 7
	s_mul_i32 s10, s2, 0x1c00000
	s_add_u32 s16, s14, 0xd600000
	s_addc_u32 s17, s15, 0
	s_add_u32 s16, s16, s10
	s_addc_u32 s17, s17, 0
	s_mul_i32 s11, s1, 0xe0000
	s_mul_i32 s30, s0, 192
	s_add_i32 s11, s11, s30
	s_add_u32 s16, s16, s11
	s_addc_u32 s17, s17, 0
	s_lshl_b32 s30, s2, 13
	s_lshl_b32 s31, s1, 8
	s_add_i32 s30, s30, s31
	s_lshl_b32 s31, s30, 7
	s_add_u32 s18, s14, 0x5100000
	s_addc_u32 s19, s15, 0
	s_add_u32 s18, s18, s31
	s_addc_u32 s19, s19, 0
	s_lshl_b32 s31, s30, 11
	s_lshl_b32 s11, s0, 7
	s_add_i32 s31, s31, s11
	s_add_u32 s26, s12, s31
	s_addc_u32 s27, s13, 0
	s_lshl_b32 s11, s0, 8
	s_add_i32 s10, s10, s11
	s_add_i32 s10, s10, 0xd600600
	s_lshl_b32 s11, s2, 19
	s_add_i32 s11, s11, 0x1de00000
	v_and_b32_e32 v1, 63, v180
	v_and_b32_e32 v178, 31, v1
	v_lshrrev_b32_e32 v179, 5, v1
	s_lshl_b32 s30, s29, 5
	v_add_u32_e32 v213, s30, v178
	s_movk_i32 s31, 0xe00
	v_mul_lo_u32 v214, v213, s31
	v_lshl_add_u32 v214, v179, 4, v214
	v_lshlrev_b32_e32 v215, 7, v213
	v_lshl_add_u32 v215, v179, 5, v215
	s_barrier
	global_load_dwordx4 v[114:117], v214, s[16:17] offset:0
	global_load_dwordx4 v[118:121], v214, s[16:17] offset:32
	global_load_dwordx4 v[122:125], v214, s[16:17] offset:64
	global_load_dwordx4 v[126:129], v214, s[16:17] offset:96
	global_load_dwordx4 v[130:133], v214, s[16:17] offset:128
	global_load_dwordx4 v[134:137], v214, s[16:17] offset:160
	global_load_dwordx4 v[34:37], v215, s[18:19]
	global_load_dwordx4 v[38:41], v215, s[18:19] offset:16
	global_load_dwordx4 v[42:45], v215, s[18:19] offset:64
	global_load_dwordx4 v[46:49], v215, s[18:19] offset:80
	v_and_b32_e32 v213, 15, v1
	v_lshrrev_b32_e32 v214, 4, v1
	s_lshl_b32 s30, s29, 3
	v_add_u32_e32 v214, s30, v214
	v_add_u32_e32 v215, 0, v214
	v_and_b32_e32 v216, 15, v215
	v_xor_b32_e32 v216, v213, v216
	v_cmp_gt_u32_e32 vcc, 8, v216
	v_and_b32_e32 v217, 7, v216
	v_mov_b32_e32 v177, 64
	v_mov_b32_e32 v1, 0xe00
	v_cndmask_b32_e32 v177, v177, v1, vcc
	v_mul_lo_u32 v177, v215, v177
	v_lshl_add_u32 v177, v217, 4, v177
	v_mov_b32_e32 v1, s11
	v_mov_b32_e32 v217, s10
	v_cndmask_b32_e32 v1, v1, v217, vcc
	v_add_u32_e32 v146, v177, v1
	v_mov_b32_e32 v1, 0x1000
	v_mov_b32_e32 v217, 0x38000
	v_cndmask_b32_e32 v148, v1, v217, vcc
	v_add_u32_e32 v215, 4, v214
	v_and_b32_e32 v216, 15, v215
	v_xor_b32_e32 v216, v213, v216
	v_cmp_gt_u32_e32 vcc, 8, v216
	v_and_b32_e32 v217, 7, v216
	v_mov_b32_e32 v177, 64
	v_mov_b32_e32 v1, 0xe00
	v_cndmask_b32_e32 v177, v177, v1, vcc
	v_mul_lo_u32 v177, v215, v177
	v_lshl_add_u32 v177, v217, 4, v177
	v_mov_b32_e32 v1, s11
	v_mov_b32_e32 v217, s10
	v_cndmask_b32_e32 v1, v1, v217, vcc
	v_add_u32_e32 v147, v177, v1
	v_mov_b32_e32 v1, 0x1000
	v_mov_b32_e32 v217, 0x38000
	v_cndmask_b32_e32 v181, v1, v217, vcc
	v_and_b32_e32 v1, 63, v180
	v_bfe_u32 v213, v1, 2, 3
	v_add_u32_e32 v213, s30, v213
	v_and_b32_e32 v214, 4, v213
	v_and_b32_e32 v215, 8, v213
	v_and_b32_e32 v213, 0xfffffff3, v213
	v_lshl_or_b32 v213, v214, 1, v213
	v_lshrrev_b32_e32 v215, 1, v215
	v_or_b32_e32 v213, v213, v215
	s_movk_i32 s31, 0xe00
	v_mul_lo_u32 v213, v213, s31
	v_and_b32_e32 v214, 3, v1
	v_lshl_add_u32 v213, v214, 4, v213
	v_lshrrev_b32_e32 v214, 5, v1
	v_lshl_add_u32 v213, v214, 6, v213
	s_add_i32 s31, s10, 128
	v_add_u32_e32 v149, s31, v213
	s_add_i32 m0, s6, 0
	s_mov_b64 exec, s[20:21]
	global_load_lds_dwordx4 v146, s[14:15]
	s_add_i32 m0, s6, 1024
	s_mov_b64 exec, s[22:23]
	global_load_lds_dwordx4 v147, s[14:15]
; __device__ __forceinline__ unsigned f2bf(float f) { unsigned u = __builtin_bit_cast(unsigned, f); return (u + 0x7fffu + ((u >> 16) & 1u)) >> 16; }
; __device__ __forceinline__ int v_st(int k, int c) { const int kk = (k & ~0xC) | ((k & 4) << 1) | ((k & 8) >> 1); return ((kk >> 3) * 4 + (c >> 5)) * 512 + ((kk & 7) * 32 + (c & 31)) * 2; }
; __device__ __forceinline__ int v_rd_base(int lane) { return ((lane & 3) << 3) | (((lane >> 2) & 3) << 6) | (((lane >> 4) & 1) << 5) | (((lane >> 5) & 1) << 8); }
; #define SWAIT() asm volatile("s_waitcnt vmcnt(0)" ::: "memory")
; __device__ __forceinline__ void attn_item(const bf16_t* __restrict__ Qb, const bf16_t* __restrict__ Kn, const bf16_t* __restrict__ Kr, const bf16_t* __restrict__ Vh,
;                                           const float* __restrict__ csq, bf16_t* __restrict__ Ob, int seq, char* lds) {
;     ...
;   const bf16_t* Qw = Qb + (long)(wid * QBLK + r32) * 1792 + hi * 8;
; #pragma unroll
;   for (int d0 = 0; d0 < 6; ++d0) qr[d0] = *reinterpret_cast<const bf16x8*>(Qw + d0 * 16);
;   { const float* cp = csq + (long)(wid * QBLK + r32) * 32 + hi * 8;
;     const f32x4 c0 = *(const f32x4*)cp, c1 = *(const f32x4*)(cp + 4), s0 = *(const f32x4*)(cp + 16), s1 = *(const f32x4*)(cp + 20);
;     float cc[8] = {c0[0], c0[1], c0[2], c0[3], c1[0], c1[1], c1[2], c1[3]}, ss[8] = {s0[0], s0[1], s0[2], s0[3], s1[0], s1[1], s1[2], s1[3]};
;     bf16x8 n4, n5;
; #pragma unroll
;     for (int e = 0; e < 8; ++e) { const float x1 = bf2f((unsigned short)qr[4][e]), x2 = bf2f((unsigned short)qr[5][e]);
;       n4[e] = (short)f2bf(x1 * cc[e] - x2 * ss[e]); n5[e] = (short)f2bf(x1 * ss[e] + x2 * cc[e]); }
;     qr[4] = n4; qr[5] = n5; }
;   const int sr = tid >> 3, sc = (tid & 7) * 8, vst0 = v_st(sr, sc);
;   const int rr_ = (tid & 255) >> 2, rc_ = (tid & 3) * 8;
;   const int vb0 = (int)(uintptr_t)V_lds + v_rd_base(lane);
;   struct { bf16x8 vs, kn, kr; } sr_[1];
;     ...
;   f32x16 pA0, pA1, pB0, pB1; float alA, alB; bf16x8 pa0, pa1, pa2, pa3; const int NT = seq / KVBLK;
;   int sp = 0, scu = 0, sn = SLOT;
;     ...
;   if (__builtin_amdgcn_readfirstlane(wid) >= 4) __builtin_amdgcn_s_setprio(1);
;   __syncthreads();
;   SLOAD(0, 0); SWAIT(); SWRITE(0, 0); __syncthreads();
;   qkt(pA0, pA1, K_lds, qr, negm, r32, hi); partialSM<true>(pA0, pA1, mhat, negm, alA);
;   SLOAD(0, KVBLK); SWAIT(); SWRITE(SLOT, 0); __syncthreads();
	s_mov_b64 exec, -1
	v_add_u32_e32 v146, v146, v148
	v_add_u32_e32 v147, v147, v181
	s_add_i32 m0, s6, 16384
	s_mov_b64 exec, s[20:21]
	global_load_lds_dwordx4 v146, s[14:15]
	s_add_i32 m0, s6, 17408
	s_mov_b64 exec, s[22:23]
	global_load_lds_dwordx4 v147, s[14:15]
	s_mov_b64 exec, -1
	v_add_u32_e32 v146, v146, v148
	v_add_u32_e32 v147, v147, v181
	s_add_i32 m0, s6, 32768
	s_mov_b64 exec, s[20:21]
	global_load_lds_dwordx4 v146, s[14:15]
	s_add_i32 m0, s6, 33792
	s_mov_b64 exec, s[22:23]
	global_load_lds_dwordx4 v147, s[14:15]
	s_mov_b64 exec, -1
	v_add_u32_e32 v146, v146, v148
	v_add_u32_e32 v147, v147, v181
	s_add_i32 m0, s7, 0
	s_nop 0
	global_load_lds_dwordx4 v149, s[14:15]
	v_add_u32_e32 v149, 0x38000, v149
	s_add_i32 m0, s6, 49152
	s_mov_b64 exec, s[20:21]
	global_load_lds_dwordx4 v146, s[14:15]
	s_add_i32 m0, s6, 50176
	s_mov_b64 exec, s[22:23]
	global_load_lds_dwordx4 v147, s[14:15]
	s_mov_b64 exec, -1
	v_add_u32_e32 v146, v146, v148
	v_add_u32_e32 v147, v147, v181
	s_add_i32 m0, s7, 16384
	s_nop 0
	global_load_lds_dwordx4 v149, s[14:15]
	v_add_u32_e32 v149, 0x38000, v149
	v_mov_b64_e32 v[2:3], 0
	v_mov_b64_e32 v[4:5], 0
	v_mov_b64_e32 v[6:7], 0
	v_mov_b64_e32 v[8:9], 0
	v_mov_b64_e32 v[10:11], 0
	v_mov_b64_e32 v[12:13], 0
	v_mov_b64_e32 v[14:15], 0
	v_mov_b64_e32 v[16:17], 0
	v_mov_b64_e32 v[18:19], 0
	v_mov_b64_e32 v[20:21], 0
	v_mov_b64_e32 v[22:23], 0
	v_mov_b64_e32 v[24:25], 0
	v_mov_b64_e32 v[26:27], 0
	v_mov_b64_e32 v[28:29], 0
	v_mov_b64_e32 v[30:31], 0
	v_mov_b64_e32 v[32:33], 0
	v_mov_b32_e32 v174, 0
	s_waitcnt vmcnt(10)
	v_lshlrev_b32_e32 v66, 16, v130
	v_and_b32_e32 v67, 0xffff0000, v130
	v_lshlrev_b32_e32 v68, 16, v131
	v_and_b32_e32 v69, 0xffff0000, v131
	v_lshlrev_b32_e32 v70, 16, v132
	v_and_b32_e32 v71, 0xffff0000, v132
	v_lshlrev_b32_e32 v72, 16, v133
	v_and_b32_e32 v73, 0xffff0000, v133
	v_lshlrev_b32_e32 v74, 16, v134
	v_and_b32_e32 v75, 0xffff0000, v134
	v_lshlrev_b32_e32 v76, 16, v135
	v_and_b32_e32 v77, 0xffff0000, v135
	v_lshlrev_b32_e32 v78, 16, v136
	v_and_b32_e32 v79, 0xffff0000, v136
	v_lshlrev_b32_e32 v80, 16, v137
	v_and_b32_e32 v81, 0xffff0000, v137
	v_mul_f32_e32 v82, v74, v42
	v_mul_f32_e32 v90, v66, v42
	v_mul_f32_e32 v83, v75, v43
	v_mul_f32_e32 v91, v67, v43
	v_mul_f32_e32 v84, v76, v44
	v_mul_f32_e32 v92, v68, v44
	v_mul_f32_e32 v85, v77, v45
	v_mul_f32_e32 v93, v69, v45
	v_mul_f32_e32 v86, v78, v46
	v_mul_f32_e32 v94, v70, v46
	v_mul_f32_e32 v87, v79, v47
	v_mul_f32_e32 v95, v71, v47
	v_mul_f32_e32 v88, v80, v48
	v_mul_f32_e32 v96, v72, v48
	v_mul_f32_e32 v89, v81, v49
	v_mul_f32_e32 v97, v73, v49
	v_fma_f32 v82, v66, v34, -v82
	v_fma_f32 v90, v74, v34, v90
	v_fma_f32 v83, v67, v35, -v83
	v_fma_f32 v91, v75, v35, v91
	v_fma_f32 v84, v68, v36, -v84
	v_fma_f32 v92, v76, v36, v92
	v_fma_f32 v85, v69, v37, -v85
	v_fma_f32 v93, v77, v37, v93
	v_fma_f32 v86, v70, v38, -v86
	v_fma_f32 v94, v78, v38, v94
	v_fma_f32 v87, v71, v39, -v87
	v_fma_f32 v95, v79, v39, v95
	v_fma_f32 v88, v72, v40, -v88
	v_fma_f32 v96, v80, v40, v96
	v_fma_f32 v89, v73, v41, -v89
	v_fma_f32 v97, v81, v41, v97
	v_cvt_pk_bf16_f32 v130, v82, v83
	v_cvt_pk_bf16_f32 v134, v90, v91
	v_cvt_pk_bf16_f32 v131, v84, v85
	v_cvt_pk_bf16_f32 v135, v92, v93
	v_cvt_pk_bf16_f32 v132, v86, v87
	v_cvt_pk_bf16_f32 v136, v94, v95
	v_cvt_pk_bf16_f32 v133, v88, v89
	v_cvt_pk_bf16_f32 v137, v96, v97
	s_waitcnt vmcnt(8)
	s_barrier
	ds_read_b128 v[182:185], v140 offset:0
	ds_read_b128 v[186:189], v140 offset:8192
	ds_read_b128 v[190:193], v141 offset:0
	ds_read_b128 v[194:197], v141 offset:8192
	ds_read_b128 v[198:201], v142 offset:0
	ds_read_b128 v[202:205], v142 offset:8192
	ds_read_b128 v[206:209], v143 offset:0
	ds_read_b128 v[210:213], v143 offset:8192
	s_waitcnt lgkmcnt(7)
	v_mfma_f32_32x32x16_bf16 v[34:49], v[182:185], v[114:117], 0
	ds_read_b128 v[182:185], v144 offset:0
	s_waitcnt lgkmcnt(7)
	v_mfma_f32_32x32x16_bf16 v[50:65], v[186:189], v[114:117], 0
	ds_read_b128 v[186:189], v144 offset:8192
	s_waitcnt lgkmcnt(7)
	v_mfma_f32_32x32x16_bf16 v[34:49], v[190:193], v[118:121], v[34:49]
	ds_read_b128 v[190:193], v145 offset:0
	s_waitcnt lgkmcnt(7)
	v_mfma_f32_32x32x16_bf16 v[50:65], v[194:197], v[118:121], v[50:65]
	ds_read_b128 v[194:197], v145 offset:8192
	s_waitcnt lgkmcnt(7)
	v_mfma_f32_32x32x16_bf16 v[34:49], v[198:201], v[122:125], v[34:49]
	s_waitcnt lgkmcnt(6)
	v_mfma_f32_32x32x16_bf16 v[50:65], v[202:205], v[122:125], v[50:65]
	s_waitcnt lgkmcnt(5)
	v_mfma_f32_32x32x16_bf16 v[34:49], v[206:209], v[126:129], v[34:49]
	s_waitcnt lgkmcnt(4)
	v_mfma_f32_32x32x16_bf16 v[50:65], v[210:213], v[126:129], v[50:65]
	s_waitcnt lgkmcnt(3)
	v_mfma_f32_32x32x16_bf16 v[34:49], v[182:185], v[130:133], v[34:49]
	s_waitcnt lgkmcnt(2)
	v_mfma_f32_32x32x16_bf16 v[50:65], v[186:189], v[130:133], v[50:65]
	s_waitcnt lgkmcnt(1)
	v_mfma_f32_32x32x16_bf16 v[34:49], v[190:193], v[134:137], v[34:49]
	s_waitcnt lgkmcnt(0)
; template <bool FIRST> __device__ __forceinline__ void partialSM(f32x16& p0, f32x16& p1, float& mhat, f32x16& negm, float& alpha) {
;   float pa = fmaxf(fmaxf(p0[0], p0[1]), p1[0]), pb = fmaxf(fmaxf(p0[2], p0[3]), p1[1]); pa = fmaxf(fmaxf(pa, p1[2]), p1[3]);
; #pragma unroll
;   for (int r = 4; r < 16; r += 4) { pa = fmaxf(fmaxf(pa, p0[r]), p0[r + 1]); pb = fmaxf(fmaxf(pb, p0[r + 2]), p0[r + 3]); pa = fmaxf(fmaxf(pa, p1[r]), p1[r + 1]); pb = fmaxf(fmaxf(pb, p1[r + 2]), p1[r + 3]); }
;   float pmax = fmaxf(pa, pb);
;   { auto rr = __builtin_amdgcn_permlane32_swap(__float_as_uint(pmax), __float_as_uint(pmax), false, false);
;     pmax = fmaxf(__uint_as_float(rr[0]), __uint_as_float(rr[1])); }
;   if (!FIRST && __builtin_expect(__all(pmax <= THRL), 1)) { alpha = 1.f; }
;   else { const float d = FIRST ? pmax : fmaxf(pmax, 0.f); mhat += d; alpha = FIRST ? 1.f : __builtin_amdgcn_exp2f(-d);
; #pragma unroll
;     for (int r = 0; r < 16; ++r) { p0[r] -= d; p1[r] -= d; }
; #pragma unroll
;     for (int r = 0; r < 16; ++r) negm[r] = -mhat; }
; #pragma unroll
;   for (int r = 0; r < 16; ++r) p0[r] = __builtin_amdgcn_exp2f(p0[r]);
; }
	v_mfma_f32_32x32x16_bf16 v[50:65], v[194:197], v[134:137], v[50:65]
	s_nop 9
	v_max3_f32 v177, v34, v35, v36
	v_max3_f32 v178, v37, v38, v39
	v_max3_f32 v177, v177, v40, v41
	v_max3_f32 v178, v178, v42, v43
	v_max3_f32 v177, v177, v44, v45
	v_max3_f32 v178, v178, v46, v47
	v_max3_f32 v177, v177, v48, v49
	v_max3_f32 v178, v178, v50, v51
	v_max3_f32 v177, v177, v52, v53
	v_max3_f32 v178, v178, v54, v55
	v_max3_f32 v177, v177, v56, v57
	v_max3_f32 v178, v178, v58, v59
	v_max3_f32 v177, v177, v60, v61
	v_max3_f32 v178, v178, v62, v63
	v_max3_f32 v177, v177, v64, v65
	v_max_f32_e32 v177, v177, v178
	v_mov_b32_e32 v178, v177
	s_nop 1
	v_permlane32_swap_b32_e32 v177, v178
	v_max_f32_e32 v177, v177, v178
	v_mov_b32_e32 v151, v177
	v_sub_f32_e32 v34, v34, v177
	v_sub_f32_e32 v35, v35, v177
	v_sub_f32_e32 v36, v36, v177
	v_sub_f32_e32 v37, v37, v177
	v_sub_f32_e32 v38, v38, v177
	v_sub_f32_e32 v39, v39, v177
	v_sub_f32_e32 v40, v40, v177
	v_sub_f32_e32 v41, v41, v177
	v_sub_f32_e32 v42, v42, v177
	v_sub_f32_e32 v43, v43, v177
	v_sub_f32_e32 v44, v44, v177
	v_sub_f32_e32 v45, v45, v177
	v_sub_f32_e32 v46, v46, v177
	v_sub_f32_e32 v47, v47, v177
	v_sub_f32_e32 v48, v48, v177
	v_sub_f32_e32 v49, v49, v177
	v_sub_f32_e32 v50, v50, v177
	v_sub_f32_e32 v51, v51, v177
	v_sub_f32_e32 v52, v52, v177
	v_sub_f32_e32 v53, v53, v177
	v_sub_f32_e32 v54, v54, v177
	v_sub_f32_e32 v55, v55, v177
	v_sub_f32_e32 v56, v56, v177
	v_sub_f32_e32 v57, v57, v177
	v_sub_f32_e32 v58, v58, v177
	v_sub_f32_e32 v59, v59, v177
	v_sub_f32_e32 v60, v60, v177
	v_sub_f32_e32 v61, v61, v177
	v_sub_f32_e32 v62, v62, v177
	v_sub_f32_e32 v63, v63, v177
	v_sub_f32_e32 v64, v64, v177
	v_sub_f32_e32 v65, v65, v177
	v_xor_b32_e32 v98, 0x80000000, v151
	v_mov_b32_e32 v99, v98
	v_mov_b32_e32 v100, v98
	v_mov_b32_e32 v101, v98
	v_mov_b32_e32 v102, v98
	v_mov_b32_e32 v103, v98
	v_mov_b32_e32 v104, v98
	v_mov_b32_e32 v105, v98
	v_mov_b32_e32 v106, v98
	v_mov_b32_e32 v107, v98
	v_mov_b32_e32 v108, v98
	v_mov_b32_e32 v109, v98
	v_mov_b32_e32 v110, v98
	v_mov_b32_e32 v111, v98
	v_mov_b32_e32 v112, v98
	v_mov_b32_e32 v113, v98
	v_exp_f32_e32 v34, v34
	v_exp_f32_e32 v35, v35
	v_exp_f32_e32 v36, v36
	v_exp_f32_e32 v37, v37
	v_exp_f32_e32 v38, v38
	v_exp_f32_e32 v39, v39
	v_exp_f32_e32 v40, v40
	v_exp_f32_e32 v41, v41
	v_exp_f32_e32 v42, v42
	v_exp_f32_e32 v43, v43
	v_exp_f32_e32 v44, v44
	v_exp_f32_e32 v45, v45
	v_exp_f32_e32 v46, v46
	v_exp_f32_e32 v47, v47
	v_exp_f32_e32 v48, v48
	v_exp_f32_e32 v49, v49
	v_add_f32_e32 v214, v34, v38
	v_add_f32_e32 v215, v35, v39
	v_add_f32_e32 v216, v36, v40
	v_add_f32_e32 v217, v37, v41
	v_add_f32_e32 v214, v214, v42
	v_add_f32_e32 v215, v215, v43
	v_add_f32_e32 v216, v216, v44
	v_add_f32_e32 v217, v217, v45
	v_add_f32_e32 v214, v214, v46
	v_add_f32_e32 v215, v215, v47
	v_add_f32_e32 v216, v216, v48
	v_add_f32_e32 v217, v217, v49
	s_waitcnt vmcnt(3)
	s_barrier
	ds_read_b128 v[182:185], v140 offset:16384
	ds_read_b128 v[186:189], v140 offset:24576
	ds_read_b128 v[190:193], v141 offset:16384
	ds_read_b128 v[194:197], v141 offset:24576
	s_mov_b32 s8, 0
; __device__ __forceinline__ void finishSM(f32x16& p0, f32x16& p1, float alpha, float& l_reg, bf16x8& pa0, bf16x8& pa1, bf16x8& pa2, bf16x8& pa3) {
; #pragma unroll
;   for (int r = 0; r < 16; ++r) p1[r] = __builtin_amdgcn_exp2f(p1[r]);
;   float ps = 0;
; #pragma unroll
;   for (int r = 0; r < 16; ++r) ps += p0[r];
; #pragma unroll
;   for (int r = 0; r < 16; ++r) ps += p1[r];
;   { auto rr = __builtin_amdgcn_permlane32_swap(__float_as_uint(ps), __float_as_uint(ps), false, false);
;     ps = __uint_as_float(rr[0]) + __uint_as_float(rr[1]); }
;   l_reg = l_reg * alpha + ps;
;     ...
;   PK4(p0, 0, pa0); PK4(p0, 8, pa1); PK4(p1, 0, pa2); PK4(p1, 8, pa3);
;     ...
; }
; __device__ __forceinline__ void qkt(f32x16& p0, f32x16& p1, const bf16_t* Ks, const bf16x8* qr, const f32x16& negm, int r32, int hi) {
;   p0 = negm; p1 = negm;
; #pragma unroll
;   for (int d0 = 0; d0 < 6; ++d0) { int cb = (d0 * 16 + hi * 8) * 2;
;     bf16x8 b0 = *reinterpret_cast<const bf16x8*>((const char*)Ks + KSWZ(r32, cb));
;     bf16x8 b1 = *reinterpret_cast<const bf16x8*>((const char*)Ks + KSWZ(32 + r32, cb));
;     p0 = __builtin_amdgcn_mfma_f32_32x32x16_bf16(b0, qr[d0], p0, 0, 0, 0);
;     p1 = __builtin_amdgcn_mfma_f32_32x32x16_bf16(b1, qr[d0], p1, 0, 0, 0); }
; }
; __device__ __forceinline__ int v_st(int k, int c) { const int kk = (k & ~0xC) | ((k & 4) << 1) | ((k & 8) >> 1); return ((kk >> 3) * 4 + (c >> 5)) * 512 + ((kk & 7) * 32 + (c & 31)) * 2; }
; __device__ __forceinline__ int v_rd_base(int lane) { return ((lane & 3) << 3) | (((lane >> 2) & 3) << 6) | (((lane >> 4) & 1) << 5) | (((lane >> 5) & 1) << 8); }
; template <int OFF> __device__ __forceinline__ s16x4 tr_read(int vb) {
;   s16x4 r; asm volatile("ds_read_b64_tr_b16 %0, %1 offset:%2" : "=&v"(r) : "v"(vb), "i"(OFF) : "memory"); return r;
; }
; template <int D0> __device__ __forceinline__ void pv_one(f32x16& od, int vb, bf16x8 pa0, bf16x8 pa1, bf16x8 pa2, bf16x8 pa3) {
;   const s16x4 l0 = tr_read<v_rd_off(D0, 0, 0)>(vb), h0 = tr_read<v_rd_off(D0, 0, 1)>(vb), l1 = tr_read<v_rd_off(D0, 1, 0)>(vb), h1 = tr_read<v_rd_off(D0, 1, 1)>(vb);
;   const s16x4 l2 = tr_read<v_rd_off(D0, 2, 0)>(vb), h2 = tr_read<v_rd_off(D0, 2, 1)>(vb), l3 = tr_read<v_rd_off(D0, 3, 0)>(vb), h3 = tr_read<v_rd_off(D0, 3, 1)>(vb);
;   asm volatile("s_waitcnt lgkmcnt(0)" ::: "memory"); SBAR();
;     ...
;   od = __builtin_amdgcn_mfma_f32_32x32x16_bf16(pa0, PK(l0, h0), od, 0, 0, 0);
.Lat_loop:
	ds_read_b128 v[198:201], v142 offset:16384
	ds_read_b128 v[202:205], v142 offset:24576
	ds_read_b128 v[206:209], v143 offset:16384
	ds_read_b128 v[210:213], v143 offset:24576
	s_add_i32 m0, s6, 0
	s_mov_b64 exec, s[20:21]
	global_load_lds_dwordx4 v146, s[14:15]
	s_add_i32 m0, s6, 1024
	s_mov_b64 exec, s[22:23]
	global_load_lds_dwordx4 v147, s[14:15]
	s_add_i32 m0, s7, 32768
	s_mov_b64 exec, -1
	global_load_lds_dwordx4 v149, s[14:15]
	v_add_u32_e32 v146, v146, v148
	v_add_u32_e32 v147, v147, v181
	v_add_u32_e32 v149, 0x38000, v149
	s_waitcnt lgkmcnt(7)
	v_mfma_f32_32x32x16_bf16 v[66:81], v[182:185], v[114:117], v[98:113]
	ds_read_b128 v[182:185], v144 offset:16384
	v_exp_f32_e32 v50, v50
	v_exp_f32_e32 v51, v51
	v_exp_f32_e32 v52, v52
	v_exp_f32_e32 v53, v53
	v_exp_f32_e32 v54, v54
	s_waitcnt lgkmcnt(7)
	v_mfma_f32_32x32x16_bf16 v[82:97], v[186:189], v[114:117], v[98:113]
	ds_read_b128 v[186:189], v144 offset:24576
	v_exp_f32_e32 v55, v55
	v_exp_f32_e32 v56, v56
	v_exp_f32_e32 v57, v57
	v_exp_f32_e32 v58, v58
	v_exp_f32_e32 v59, v59
	s_waitcnt lgkmcnt(7)
	v_mfma_f32_32x32x16_bf16 v[66:81], v[190:193], v[118:121], v[66:81]
	ds_read_b128 v[190:193], v145 offset:16384
	v_exp_f32_e32 v60, v60
	v_exp_f32_e32 v61, v61
	v_exp_f32_e32 v62, v62
	v_exp_f32_e32 v63, v63
	v_exp_f32_e32 v64, v64
	s_waitcnt lgkmcnt(7)
	v_mfma_f32_32x32x16_bf16 v[82:97], v[194:197], v[118:121], v[82:97]
	ds_read_b128 v[194:197], v145 offset:24576
	v_exp_f32_e32 v65, v65
	v_cvt_pk_bf16_f32 v158, v34, v35
	v_cvt_pk_bf16_f32 v159, v36, v37
	v_cvt_pk_bf16_f32 v160, v38, v39
	v_cvt_pk_bf16_f32 v161, v40, v41
	s_waitcnt lgkmcnt(7)
	v_mfma_f32_32x32x16_bf16 v[66:81], v[198:201], v[122:125], v[66:81]
	ds_read_b64_tr_b16 v[198:199], v150 offset:8192
	ds_read_b64_tr_b16 v[200:201], v150 offset:10240
	v_cvt_pk_bf16_f32 v162, v42, v43
	v_cvt_pk_bf16_f32 v163, v44, v45
	v_cvt_pk_bf16_f32 v164, v46, v47
	v_cvt_pk_bf16_f32 v165, v48, v49
	v_permlane32_swap_b32_e32 v158, v160
	s_waitcnt lgkmcnt(8)
	v_mfma_f32_32x32x16_bf16 v[82:97], v[202:205], v[122:125], v[82:97]
	ds_read_b64_tr_b16 v[202:203], v150 offset:8704
	ds_read_b64_tr_b16 v[204:205], v150 offset:10752
	v_permlane32_swap_b32_e32 v159, v161
	v_permlane32_swap_b32_e32 v162, v164
	v_permlane32_swap_b32_e32 v163, v165
	v_add_f32_e32 v214, v214, v50
	v_add_f32_e32 v215, v215, v51
	s_waitcnt lgkmcnt(9)
	v_mfma_f32_32x32x16_bf16 v[66:81], v[206:209], v[126:129], v[66:81]
	ds_read_b64_tr_b16 v[206:207], v150 offset:12288
	ds_read_b64_tr_b16 v[208:209], v150 offset:14336
	v_add_f32_e32 v216, v216, v52
	v_add_f32_e32 v217, v217, v53
	v_add_f32_e32 v214, v214, v54
	v_add_f32_e32 v215, v215, v55
	v_add_f32_e32 v216, v216, v56
	s_waitcnt lgkmcnt(10)
	v_mfma_f32_32x32x16_bf16 v[82:97], v[210:213], v[126:129], v[82:97]
	ds_read_b64_tr_b16 v[210:211], v150 offset:12800
	ds_read_b64_tr_b16 v[212:213], v150 offset:14848
	v_add_f32_e32 v217, v217, v57
	v_add_f32_e32 v214, v214, v58
	v_add_f32_e32 v215, v215, v59
	v_add_f32_e32 v216, v216, v60
	v_add_f32_e32 v217, v217, v61
	s_waitcnt lgkmcnt(11)
	v_mfma_f32_32x32x16_bf16 v[66:81], v[182:185], v[130:133], v[66:81]
	ds_read_b64_tr_b16 v[182:183], v150 offset:0
	ds_read_b64_tr_b16 v[184:185], v150 offset:2048
	v_add_f32_e32 v214, v214, v62
	v_add_f32_e32 v215, v215, v63
	v_add_f32_e32 v216, v216, v64
	v_add_f32_e32 v217, v217, v65
	v_add_f32_e32 v214, v214, v215
	s_waitcnt lgkmcnt(12)
	v_mfma_f32_32x32x16_bf16 v[82:97], v[186:189], v[130:133], v[82:97]
	ds_read_b64_tr_b16 v[186:187], v150 offset:512
	ds_read_b64_tr_b16 v[188:189], v150 offset:2560
	v_add_f32_e32 v216, v216, v217
	v_add_f32_e32 v214, v214, v216
	v_add_f32_e32 v174, v174, v214
	v_cvt_pk_bf16_f32 v166, v50, v51
	v_cvt_pk_bf16_f32 v167, v52, v53
	s_waitcnt lgkmcnt(13)
	v_mfma_f32_32x32x16_bf16 v[66:81], v[190:193], v[134:137], v[66:81]
	ds_read_b64_tr_b16 v[190:191], v150 offset:4096
	ds_read_b64_tr_b16 v[192:193], v150 offset:6144
	v_cvt_pk_bf16_f32 v168, v54, v55
	v_cvt_pk_bf16_f32 v169, v56, v57
	v_cvt_pk_bf16_f32 v170, v58, v59
	v_cvt_pk_bf16_f32 v171, v60, v61
	v_cvt_pk_bf16_f32 v172, v62, v63
	s_waitcnt lgkmcnt(14)
	v_mfma_f32_32x32x16_bf16 v[82:97], v[194:197], v[134:137], v[82:97]
	ds_read_b64_tr_b16 v[194:195], v150 offset:4608
	ds_read_b64_tr_b16 v[196:197], v150 offset:6656
	v_cvt_pk_bf16_f32 v173, v64, v65
	v_permlane32_swap_b32_e32 v166, v168
	v_permlane32_swap_b32_e32 v167, v169
	v_permlane32_swap_b32_e32 v170, v172
	v_permlane32_swap_b32_e32 v171, v173
	s_waitcnt lgkmcnt(6)
	v_mfma_f32_32x32x16_bf16 v[2:17], v[158:161], v[182:185], v[2:17]
	ds_read_b128 v[182:185], v140 offset:32768
	v_max3_f32 v177, v66, v67, v68
	v_max3_f32 v178, v69, v70, v71
	v_max3_f32 v177, v177, v72, v73
	s_waitcnt lgkmcnt(5)
	v_mfma_f32_32x32x16_bf16 v[18:33], v[158:161], v[186:189], v[18:33]
	ds_read_b128 v[186:189], v140 offset:40960
	v_max3_f32 v178, v178, v74, v75
	v_max3_f32 v177, v177, v76, v77
	v_max3_f32 v178, v178, v78, v79
	v_max3_f32 v177, v177, v80, v81
	v_max3_f32 v178, v178, v82, v83
	v_max3_f32 v177, v177, v84, v85
	s_waitcnt lgkmcnt(4)
	v_mfma_f32_32x32x16_bf16 v[2:17], v[162:165], v[190:193], v[2:17]
	ds_read_b128 v[190:193], v141 offset:32768
	v_max3_f32 v178, v178, v86, v87
	v_max3_f32 v177, v177, v88, v89
	v_max3_f32 v178, v178, v90, v91
	v_max3_f32 v177, v177, v92, v93
	v_max3_f32 v178, v178, v94, v95
	v_max3_f32 v177, v177, v96, v97
	s_waitcnt lgkmcnt(3)
	v_mfma_f32_32x32x16_bf16 v[18:33], v[162:165], v[194:197], v[18:33]
	ds_read_b128 v[194:197], v141 offset:40960
	v_max_f32_e32 v177, v177, v178
	v_mov_b32_e32 v178, v177
	s_nop 1
	v_permlane32_swap_b32_e32 v177, v178
	v_max_f32_e32 v177, v177, v178
	v_cmp_ge_f32_e32 vcc, 0x4138aa3b, v177
	s_cmp_eq_u64 vcc, exec
	s_cbranch_scc0 .Lat_rare1_2

; __device__ __forceinline__ void finishSM(f32x16& p0, f32x16& p1, float alpha, float& l_reg, bf16x8& pa0, bf16x8& pa1, bf16x8& pa2, bf16x8& pa3) {
; #pragma unroll
;   for (int r = 0; r < 16; ++r) p1[r] = __builtin_amdgcn_exp2f(p1[r]);
;   float ps = 0;
; #pragma unroll
;   for (int r = 0; r < 16; ++r) ps += p0[r];
; #pragma unroll
;   for (int r = 0; r < 16; ++r) ps += p1[r];
;   { auto rr = __builtin_amdgcn_permlane32_swap(__float_as_uint(ps), __float_as_uint(ps), false, false);
;     ps = __uint_as_float(rr[0]) + __uint_as_float(rr[1]); }
;   l_reg = l_reg * alpha + ps;
;     ...
;   PK4(p0, 0, pa0); PK4(p0, 8, pa1); PK4(p1, 0, pa2); PK4(p1, 8, pa3);
;     ...
; }
; __device__ __forceinline__ void qkt(f32x16& p0, f32x16& p1, const bf16_t* Ks, const bf16x8* qr, const f32x16& negm, int r32, int hi) {
;   p0 = negm; p1 = negm;
; #pragma unroll
;   for (int d0 = 0; d0 < 6; ++d0) { int cb = (d0 * 16 + hi * 8) * 2;
;     bf16x8 b0 = *reinterpret_cast<const bf16x8*>((const char*)Ks + KSWZ(r32, cb));
;     bf16x8 b1 = *reinterpret_cast<const bf16x8*>((const char*)Ks + KSWZ(32 + r32, cb));
;     p0 = __builtin_amdgcn_mfma_f32_32x32x16_bf16(b0, qr[d0], p0, 0, 0, 0);
;     p1 = __builtin_amdgcn_mfma_f32_32x32x16_bf16(b1, qr[d0], p1, 0, 0, 0); }
; }
; __device__ __forceinline__ int v_st(int k, int c) { const int kk = (k & ~0xC) | ((k & 4) << 1) | ((k & 8) >> 1); return ((kk >> 3) * 4 + (c >> 5)) * 512 + ((kk & 7) * 32 + (c & 31)) * 2; }
; __device__ __forceinline__ int v_rd_base(int lane) { return ((lane & 3) << 3) | (((lane >> 2) & 3) << 6) | (((lane >> 4) & 1) << 5) | (((lane >> 5) & 1) << 8); }
; template <int OFF> __device__ __forceinline__ s16x4 tr_read(int vb) {
;   s16x4 r; asm volatile("ds_read_b64_tr_b16 %0, %1 offset:%2" : "=&v"(r) : "v"(vb), "i"(OFF) : "memory"); return r;
; }
; template <int D0> __device__ __forceinline__ void pv_one(f32x16& od, int vb, bf16x8 pa0, bf16x8 pa1, bf16x8 pa2, bf16x8 pa3) {
;   const s16x4 l0 = tr_read<v_rd_off(D0, 0, 0)>(vb), h0 = tr_read<v_rd_off(D0, 0, 1)>(vb), l1 = tr_read<v_rd_off(D0, 1, 0)>(vb), h1 = tr_read<v_rd_off(D0, 1, 1)>(vb);
;   const s16x4 l2 = tr_read<v_rd_off(D0, 2, 0)>(vb), h2 = tr_read<v_rd_off(D0, 2, 1)>(vb), l3 = tr_read<v_rd_off(D0, 3, 0)>(vb), h3 = tr_read<v_rd_off(D0, 3, 1)>(vb);
;   asm volatile("s_waitcnt lgkmcnt(0)" ::: "memory"); SBAR();
;     ...
;   od = __builtin_amdgcn_mfma_f32_32x32x16_bf16(pa0, PK(l0, h0), od, 0, 0, 0);
.Lat_rr_4:
	s_waitcnt lgkmcnt(0)
	s_barrier
	ds_read_b128 v[198:201], v142 offset:32768
	ds_read_b128 v[202:205], v142 offset:40960
	ds_read_b128 v[206:209], v143 offset:32768
	ds_read_b128 v[210:213], v143 offset:40960
	s_add_i32 m0, s6, 16384
	s_mov_b64 exec, s[20:21]
	global_load_lds_dwordx4 v146, s[14:15]
	s_add_i32 m0, s6, 17408
	s_mov_b64 exec, s[22:23]
	global_load_lds_dwordx4 v147, s[14:15]
	s_add_i32 m0, s7, 49152
	s_mov_b64 exec, -1
	global_load_lds_dwordx4 v149, s[14:15]
	v_add_u32_e32 v146, v146, v148
	v_add_u32_e32 v147, v147, v181
	v_add_u32_e32 v149, 0x38000, v149
	v_mfma_f32_32x32x16_bf16 v[34:49], v[182:185], v[114:117], v[98:113]
	ds_read_b128 v[182:185], v144 offset:32768
	v_exp_f32_e32 v82, v82
	v_exp_f32_e32 v83, v83
	v_exp_f32_e32 v84, v84
	v_exp_f32_e32 v85, v85
	v_exp_f32_e32 v86, v86
	v_mfma_f32_32x32x16_bf16 v[50:65], v[186:189], v[114:117], v[98:113]
	ds_read_b128 v[186:189], v144 offset:40960
	v_exp_f32_e32 v87, v87
	v_exp_f32_e32 v88, v88
	v_exp_f32_e32 v89, v89
	v_exp_f32_e32 v90, v90
	v_exp_f32_e32 v91, v91
	v_mfma_f32_32x32x16_bf16 v[34:49], v[190:193], v[118:121], v[34:49]
	ds_read_b128 v[190:193], v145 offset:32768
	v_exp_f32_e32 v92, v92
	v_exp_f32_e32 v93, v93
	v_exp_f32_e32 v94, v94
	v_exp_f32_e32 v95, v95
	v_exp_f32_e32 v96, v96
	v_mfma_f32_32x32x16_bf16 v[50:65], v[194:197], v[118:121], v[50:65]
	ds_read_b128 v[194:197], v145 offset:40960
	v_exp_f32_e32 v97, v97
	v_cvt_pk_bf16_f32 v158, v66, v67
	v_cvt_pk_bf16_f32 v159, v68, v69
	v_cvt_pk_bf16_f32 v160, v70, v71
	v_cvt_pk_bf16_f32 v161, v72, v73
	s_waitcnt lgkmcnt(7)
	v_mfma_f32_32x32x16_bf16 v[34:49], v[198:201], v[122:125], v[34:49]
	ds_read_b64_tr_b16 v[198:199], v150 offset:24576
	ds_read_b64_tr_b16 v[200:201], v150 offset:26624
	v_cvt_pk_bf16_f32 v162, v74, v75
	v_cvt_pk_bf16_f32 v163, v76, v77
	v_cvt_pk_bf16_f32 v164, v78, v79
	v_cvt_pk_bf16_f32 v165, v80, v81
	v_permlane32_swap_b32_e32 v158, v160
	s_waitcnt lgkmcnt(8)
	v_mfma_f32_32x32x16_bf16 v[50:65], v[202:205], v[122:125], v[50:65]
	ds_read_b64_tr_b16 v[202:203], v150 offset:25088
	ds_read_b64_tr_b16 v[204:205], v150 offset:27136
	v_permlane32_swap_b32_e32 v159, v161
	v_permlane32_swap_b32_e32 v162, v164
	v_permlane32_swap_b32_e32 v163, v165
	v_add_f32_e32 v214, v214, v82
	v_add_f32_e32 v215, v215, v83
	s_waitcnt lgkmcnt(9)
	v_mfma_f32_32x32x16_bf16 v[34:49], v[206:209], v[126:129], v[34:49]
	ds_read_b64_tr_b16 v[206:207], v150 offset:28672
	ds_read_b64_tr_b16 v[208:209], v150 offset:30720
	v_add_f32_e32 v216, v216, v84
	v_add_f32_e32 v217, v217, v85
	v_add_f32_e32 v214, v214, v86
	v_add_f32_e32 v215, v215, v87
	v_add_f32_e32 v216, v216, v88
	s_waitcnt lgkmcnt(10)
	v_mfma_f32_32x32x16_bf16 v[50:65], v[210:213], v[126:129], v[50:65]
	ds_read_b64_tr_b16 v[210:211], v150 offset:29184
	ds_read_b64_tr_b16 v[212:213], v150 offset:31232
	v_add_f32_e32 v217, v217, v89
	v_add_f32_e32 v214, v214, v90
	v_add_f32_e32 v215, v215, v91
	v_add_f32_e32 v216, v216, v92
	v_add_f32_e32 v217, v217, v93
	s_waitcnt lgkmcnt(11)
	v_mfma_f32_32x32x16_bf16 v[34:49], v[182:185], v[130:133], v[34:49]
	ds_read_b64_tr_b16 v[182:183], v150 offset:16384
	ds_read_b64_tr_b16 v[184:185], v150 offset:18432
	v_add_f32_e32 v214, v214, v94
	v_add_f32_e32 v215, v215, v95
	v_add_f32_e32 v216, v216, v96
	v_add_f32_e32 v217, v217, v97
	v_add_f32_e32 v214, v214, v215
	s_waitcnt lgkmcnt(12)
	v_mfma_f32_32x32x16_bf16 v[50:65], v[186:189], v[130:133], v[50:65]
	ds_read_b64_tr_b16 v[186:187], v150 offset:16896
	ds_read_b64_tr_b16 v[188:189], v150 offset:18944
	v_add_f32_e32 v216, v216, v217
	v_add_f32_e32 v214, v214, v216
	v_add_f32_e32 v174, v174, v214
	v_cvt_pk_bf16_f32 v166, v82, v83
	v_cvt_pk_bf16_f32 v167, v84, v85
	s_waitcnt lgkmcnt(13)
	v_mfma_f32_32x32x16_bf16 v[34:49], v[190:193], v[134:137], v[34:49]
	ds_read_b64_tr_b16 v[190:191], v150 offset:20480
	ds_read_b64_tr_b16 v[192:193], v150 offset:22528
	v_cvt_pk_bf16_f32 v168, v86, v87
	v_cvt_pk_bf16_f32 v169, v88, v89
	v_cvt_pk_bf16_f32 v170, v90, v91
	v_cvt_pk_bf16_f32 v171, v92, v93
	v_cvt_pk_bf16_f32 v172, v94, v95
	s_waitcnt lgkmcnt(14)
	v_mfma_f32_32x32x16_bf16 v[50:65], v[194:197], v[134:137], v[50:65]
	ds_read_b64_tr_b16 v[194:195], v150 offset:20992
	ds_read_b64_tr_b16 v[196:197], v150 offset:23040
	v_cvt_pk_bf16_f32 v173, v96, v97
	v_permlane32_swap_b32_e32 v166, v168
	v_permlane32_swap_b32_e32 v167, v169
	v_permlane32_swap_b32_e32 v170, v172
	v_permlane32_swap_b32_e32 v171, v173
	s_waitcnt lgkmcnt(6)
	v_mfma_f32_32x32x16_bf16 v[2:17], v[158:161], v[182:185], v[2:17]
	ds_read_b128 v[182:185], v140 offset:49152
	v_max3_f32 v177, v34, v35, v36
	v_max3_f32 v178, v37, v38, v39
	v_max3_f32 v177, v177, v40, v41
	s_waitcnt lgkmcnt(5)
	v_mfma_f32_32x32x16_bf16 v[18:33], v[158:161], v[186:189], v[18:33]
	ds_read_b128 v[186:189], v140 offset:57344
	v_max3_f32 v178, v178, v42, v43
	v_max3_f32 v177, v177, v44, v45
	v_max3_f32 v178, v178, v46, v47
	v_max3_f32 v177, v177, v48, v49
	v_max3_f32 v178, v178, v50, v51
	v_max3_f32 v177, v177, v52, v53
	s_waitcnt lgkmcnt(4)
	v_mfma_f32_32x32x16_bf16 v[2:17], v[162:165], v[190:193], v[2:17]
	ds_read_b128 v[190:193], v141 offset:49152
	v_max3_f32 v178, v178, v54, v55
	v_max3_f32 v177, v177, v56, v57
	v_max3_f32 v178, v178, v58, v59
	v_max3_f32 v177, v177, v60, v61
	v_max3_f32 v178, v178, v62, v63
	v_max3_f32 v177, v177, v64, v65
	s_waitcnt lgkmcnt(3)
	v_mfma_f32_32x32x16_bf16 v[18:33], v[162:165], v[194:197], v[18:33]
	ds_read_b128 v[194:197], v141 offset:57344
	v_max_f32_e32 v177, v177, v178
	v_mov_b32_e32 v178, v177
	s_nop 1
	v_permlane32_swap_b32_e32 v177, v178
	v_max_f32_e32 v177, v177, v178
	v_cmp_ge_f32_e32 vcc, 0x4138aa3b, v177
	s_cmp_eq_u64 vcc, exec
	s_cbranch_scc0 .Lat_rare1_6

; template <bool FIRST> __device__ __forceinline__ void partialSM(f32x16& p0, f32x16& p1, float& mhat, f32x16& negm, float& alpha) {
;   float pa = fmaxf(fmaxf(p0[0], p0[1]), p1[0]), pb = fmaxf(fmaxf(p0[2], p0[3]), p1[1]); pa = fmaxf(fmaxf(pa, p1[2]), p1[3]);
; #pragma unroll
;   for (int r = 4; r < 16; r += 4) { pa = fmaxf(fmaxf(pa, p0[r]), p0[r + 1]); pb = fmaxf(fmaxf(pb, p0[r + 2]), p0[r + 3]); pa = fmaxf(fmaxf(pa, p1[r]), p1[r + 1]); pb = fmaxf(fmaxf(pb, p1[r + 2]), p1[r + 3]); }
;   float pmax = fmaxf(pa, pb);
;   { auto rr = __builtin_amdgcn_permlane32_swap(__float_as_uint(pmax), __float_as_uint(pmax), false, false);
;     pmax = fmaxf(__uint_as_float(rr[0]), __uint_as_float(rr[1])); }
;   if (!FIRST && __builtin_expect(__all(pmax <= THRL), 1)) { alpha = 1.f; }
;   else { const float d = FIRST ? pmax : fmaxf(pmax, 0.f); mhat += d; alpha = FIRST ? 1.f : __builtin_amdgcn_exp2f(-d);
; #pragma unroll
;     for (int r = 0; r < 16; ++r) { p0[r] -= d; p1[r] -= d; }
; #pragma unroll
;     for (int r = 0; r < 16; ++r) negm[r] = -mhat; }
; #pragma unroll
;   for (int r = 0; r < 16; ++r) p0[r] = __builtin_amdgcn_exp2f(p0[r]);
; }
; __device__ __forceinline__ void finishSM(f32x16& p0, f32x16& p1, float alpha, float& l_reg, bf16x8& pa0, bf16x8& pa1, bf16x8& pa2, bf16x8& pa3) {
; #pragma unroll
;   for (int r = 0; r < 16; ++r) p1[r] = __builtin_amdgcn_exp2f(p1[r]);
;   float ps = 0;
; #pragma unroll
;   for (int r = 0; r < 16; ++r) ps += p0[r];
; #pragma unroll
;   for (int r = 0; r < 16; ++r) ps += p1[r];
;   { auto rr = __builtin_amdgcn_permlane32_swap(__float_as_uint(ps), __float_as_uint(ps), false, false);
;     ps = __uint_as_float(rr[0]) + __uint_as_float(rr[1]); }
;   l_reg = l_reg * alpha + ps;
;     ...
;   PK4(p0, 0, pa0); PK4(p0, 8, pa1); PK4(p1, 0, pa2); PK4(p1, 8, pa3);
;     ...
; }
; __device__ __forceinline__ void qkt(f32x16& p0, f32x16& p1, const bf16_t* Ks, const bf16x8* qr, const f32x16& negm, int r32, int hi) {
;   p0 = negm; p1 = negm;
; #pragma unroll
;   for (int d0 = 0; d0 < 6; ++d0) { int cb = (d0 * 16 + hi * 8) * 2;
;     bf16x8 b0 = *reinterpret_cast<const bf16x8*>((const char*)Ks + KSWZ(r32, cb));
;     bf16x8 b1 = *reinterpret_cast<const bf16x8*>((const char*)Ks + KSWZ(32 + r32, cb));
;     p0 = __builtin_amdgcn_mfma_f32_32x32x16_bf16(b0, qr[d0], p0, 0, 0, 0);
;     p1 = __builtin_amdgcn_mfma_f32_32x32x16_bf16(b1, qr[d0], p1, 0, 0, 0); }
; }
.Lat_rr_8:
	s_waitcnt lgkmcnt(0)
	s_barrier
	ds_read_b128 v[198:201], v142 offset:49152
	ds_read_b128 v[202:205], v142 offset:57344
	ds_read_b128 v[206:209], v143 offset:49152
	ds_read_b128 v[210:213], v143 offset:57344
	s_add_i32 m0, s6, 32768
	s_mov_b64 exec, s[20:21]
	global_load_lds_dwordx4 v146, s[14:15]
	s_add_i32 m0, s6, 33792
	s_mov_b64 exec, s[22:23]
	global_load_lds_dwordx4 v147, s[14:15]
	s_add_i32 m0, s7, 0
	s_mov_b64 exec, -1
	global_load_lds_dwordx4 v149, s[14:15]
	v_add_u32_e32 v146, v146, v148
	v_add_u32_e32 v147, v147, v181
	v_add_u32_e32 v149, 0x38000, v149
	v_mfma_f32_32x32x16_bf16 v[66:81], v[182:185], v[114:117], v[98:113]
	ds_read_b128 v[182:185], v144 offset:49152
	v_exp_f32_e32 v50, v50
	v_exp_f32_e32 v51, v51
	v_exp_f32_e32 v52, v52
	v_exp_f32_e32 v53, v53
	v_exp_f32_e32 v54, v54
	v_mfma_f32_32x32x16_bf16 v[82:97], v[186:189], v[114:117], v[98:113]
	ds_read_b128 v[186:189], v144 offset:57344
	v_exp_f32_e32 v55, v55
	v_exp_f32_e32 v56, v56
	v_exp_f32_e32 v57, v57
	v_exp_f32_e32 v58, v58
	v_exp_f32_e32 v59, v59
	v_mfma_f32_32x32x16_bf16 v[66:81], v[190:193], v[118:121], v[66:81]
	ds_read_b128 v[190:193], v145 offset:49152
	v_exp_f32_e32 v60, v60
	v_exp_f32_e32 v61, v61
	v_exp_f32_e32 v62, v62
	v_exp_f32_e32 v63, v63
	v_exp_f32_e32 v64, v64
	v_mfma_f32_32x32x16_bf16 v[82:97], v[194:197], v[118:121], v[82:97]
	ds_read_b128 v[194:197], v145 offset:57344
	v_exp_f32_e32 v65, v65
	v_cvt_pk_bf16_f32 v158, v34, v35
	v_cvt_pk_bf16_f32 v159, v36, v37
	v_cvt_pk_bf16_f32 v160, v38, v39
	v_cvt_pk_bf16_f32 v161, v40, v41
	s_waitcnt lgkmcnt(7)
	v_mfma_f32_32x32x16_bf16 v[66:81], v[198:201], v[122:125], v[66:81]
	ds_read_b64_tr_b16 v[198:199], v150 offset:40960
	ds_read_b64_tr_b16 v[200:201], v150 offset:43008
	v_cvt_pk_bf16_f32 v162, v42, v43
	v_cvt_pk_bf16_f32 v163, v44, v45
	v_cvt_pk_bf16_f32 v164, v46, v47
	v_cvt_pk_bf16_f32 v165, v48, v49
	v_permlane32_swap_b32_e32 v158, v160
	s_waitcnt lgkmcnt(8)
	v_mfma_f32_32x32x16_bf16 v[82:97], v[202:205], v[122:125], v[82:97]
	ds_read_b64_tr_b16 v[202:203], v150 offset:41472
	ds_read_b64_tr_b16 v[204:205], v150 offset:43520
	v_permlane32_swap_b32_e32 v159, v161
	v_permlane32_swap_b32_e32 v162, v164
	v_permlane32_swap_b32_e32 v163, v165
	v_add_f32_e32 v214, v214, v50
	v_add_f32_e32 v215, v215, v51
	s_waitcnt lgkmcnt(9)
	v_mfma_f32_32x32x16_bf16 v[66:81], v[206:209], v[126:129], v[66:81]
	ds_read_b64_tr_b16 v[206:207], v150 offset:45056
	ds_read_b64_tr_b16 v[208:209], v150 offset:47104
	v_add_f32_e32 v216, v216, v52
	v_add_f32_e32 v217, v217, v53
	v_add_f32_e32 v214, v214, v54
	v_add_f32_e32 v215, v215, v55
	v_add_f32_e32 v216, v216, v56
	s_waitcnt lgkmcnt(10)
	v_mfma_f32_32x32x16_bf16 v[82:97], v[210:213], v[126:129], v[82:97]
	ds_read_b64_tr_b16 v[210:211], v150 offset:45568
	ds_read_b64_tr_b16 v[212:213], v150 offset:47616
	v_add_f32_e32 v217, v217, v57
	v_add_f32_e32 v214, v214, v58
	v_add_f32_e32 v215, v215, v59
	v_add_f32_e32 v216, v216, v60
	v_add_f32_e32 v217, v217, v61
	s_waitcnt lgkmcnt(11)
	v_mfma_f32_32x32x16_bf16 v[66:81], v[182:185], v[130:133], v[66:81]
	ds_read_b64_tr_b16 v[182:183], v150 offset:32768
	ds_read_b64_tr_b16 v[184:185], v150 offset:34816
	v_add_f32_e32 v214, v214, v62
	v_add_f32_e32 v215, v215, v63
	v_add_f32_e32 v216, v216, v64
	v_add_f32_e32 v217, v217, v65
	v_add_f32_e32 v214, v214, v215
	s_waitcnt lgkmcnt(12)
	v_mfma_f32_32x32x16_bf16 v[82:97], v[186:189], v[130:133], v[82:97]
	ds_read_b64_tr_b16 v[186:187], v150 offset:33280
	ds_read_b64_tr_b16 v[188:189], v150 offset:35328
	v_add_f32_e32 v216, v216, v217
	v_add_f32_e32 v214, v214, v216
	v_add_f32_e32 v174, v174, v214
	v_cvt_pk_bf16_f32 v166, v50, v51
	v_cvt_pk_bf16_f32 v167, v52, v53
	s_waitcnt lgkmcnt(13)
	v_mfma_f32_32x32x16_bf16 v[66:81], v[190:193], v[134:137], v[66:81]
	ds_read_b64_tr_b16 v[190:191], v150 offset:36864
	ds_read_b64_tr_b16 v[192:193], v150 offset:38912
	v_cvt_pk_bf16_f32 v168, v54, v55
	v_cvt_pk_bf16_f32 v169, v56, v57
	v_cvt_pk_bf16_f32 v170, v58, v59
	v_cvt_pk_bf16_f32 v171, v60, v61
	v_cvt_pk_bf16_f32 v172, v62, v63
	s_waitcnt lgkmcnt(14)
	v_mfma_f32_32x32x16_bf16 v[82:97], v[194:197], v[134:137], v[82:97]
	ds_read_b64_tr_b16 v[194:195], v150 offset:37376
	ds_read_b64_tr_b16 v[196:197], v150 offset:39424
	v_cvt_pk_bf16_f32 v173, v64, v65
	v_permlane32_swap_b32_e32 v166, v168
	v_permlane32_swap_b32_e32 v167, v169
	v_permlane32_swap_b32_e32 v170, v172
	v_permlane32_swap_b32_e32 v171, v173
	s_waitcnt lgkmcnt(6)
	v_mfma_f32_32x32x16_bf16 v[2:17], v[158:161], v[182:185], v[2:17]
	ds_read_b128 v[182:185], v140 offset:0
	v_max3_f32 v177, v66, v67, v68
	v_max3_f32 v178, v69, v70, v71
	v_max3_f32 v177, v177, v72, v73
	s_waitcnt lgkmcnt(5)
	v_mfma_f32_32x32x16_bf16 v[18:33], v[158:161], v[186:189], v[18:33]
	ds_read_b128 v[186:189], v140 offset:8192
	v_max3_f32 v178, v178, v74, v75
	v_max3_f32 v177, v177, v76, v77
	v_max3_f32 v178, v178, v78, v79
	v_max3_f32 v177, v177, v80, v81
	v_max3_f32 v178, v178, v82, v83
	v_max3_f32 v177, v177, v84, v85
	s_waitcnt lgkmcnt(4)
	v_mfma_f32_32x32x16_bf16 v[2:17], v[162:165], v[190:193], v[2:17]
	ds_read_b128 v[190:193], v141 offset:0
	v_max3_f32 v178, v178, v86, v87
	v_max3_f32 v177, v177, v88, v89
	v_max3_f32 v178, v178, v90, v91
	v_max3_f32 v177, v177, v92, v93
	v_max3_f32 v178, v178, v94, v95
	v_max3_f32 v177, v177, v96, v97
	s_waitcnt lgkmcnt(3)
	v_mfma_f32_32x32x16_bf16 v[18:33], v[162:165], v[194:197], v[18:33]
	ds_read_b128 v[194:197], v141 offset:8192
	v_max_f32_e32 v177, v177, v178
	v_mov_b32_e32 v178, v177
	s_nop 1
	v_permlane32_swap_b32_e32 v177, v178
	v_max_f32_e32 v177, v177, v178
	v_cmp_ge_f32_e32 vcc, 0x4138aa3b, v177
	s_cmp_eq_u64 vcc, exec
	s_cbranch_scc0 .Lat_rare1_10

; template <bool FIRST> __device__ __forceinline__ void partialSM(f32x16& p0, f32x16& p1, float& mhat, f32x16& negm, float& alpha) {
;   float pa = fmaxf(fmaxf(p0[0], p0[1]), p1[0]), pb = fmaxf(fmaxf(p0[2], p0[3]), p1[1]); pa = fmaxf(fmaxf(pa, p1[2]), p1[3]);
; #pragma unroll
;   for (int r = 4; r < 16; r += 4) { pa = fmaxf(fmaxf(pa, p0[r]), p0[r + 1]); pb = fmaxf(fmaxf(pb, p0[r + 2]), p0[r + 3]); pa = fmaxf(fmaxf(pa, p1[r]), p1[r + 1]); pb = fmaxf(fmaxf(pb, p1[r + 2]), p1[r + 3]); }
;   float pmax = fmaxf(pa, pb);
;   { auto rr = __builtin_amdgcn_permlane32_swap(__float_as_uint(pmax), __float_as_uint(pmax), false, false);
;     pmax = fmaxf(__uint_as_float(rr[0]), __uint_as_float(rr[1])); }
;   if (!FIRST && __builtin_expect(__all(pmax <= THRL), 1)) { alpha = 1.f; }
;   else { const float d = FIRST ? pmax : fmaxf(pmax, 0.f); mhat += d; alpha = FIRST ? 1.f : __builtin_amdgcn_exp2f(-d);
; #pragma unroll
;     for (int r = 0; r < 16; ++r) { p0[r] -= d; p1[r] -= d; }
; #pragma unroll
;     for (int r = 0; r < 16; ++r) negm[r] = -mhat; }
; #pragma unroll
;   for (int r = 0; r < 16; ++r) p0[r] = __builtin_amdgcn_exp2f(p0[r]);
; }
; __device__ __forceinline__ void finishSM(f32x16& p0, f32x16& p1, float alpha, float& l_reg, bf16x8& pa0, bf16x8& pa1, bf16x8& pa2, bf16x8& pa3) {
; #pragma unroll
;   for (int r = 0; r < 16; ++r) p1[r] = __builtin_amdgcn_exp2f(p1[r]);
;   float ps = 0;
; #pragma unroll
;   for (int r = 0; r < 16; ++r) ps += p0[r];
; #pragma unroll
;   for (int r = 0; r < 16; ++r) ps += p1[r];
;   { auto rr = __builtin_amdgcn_permlane32_swap(__float_as_uint(ps), __float_as_uint(ps), false, false);
;     ps = __uint_as_float(rr[0]) + __uint_as_float(rr[1]); }
;   l_reg = l_reg * alpha + ps;
;     ...
;   PK4(p0, 0, pa0); PK4(p0, 8, pa1); PK4(p1, 0, pa2); PK4(p1, 8, pa3);
;     ...
; }
; __device__ __forceinline__ void qkt(f32x16& p0, f32x16& p1, const bf16_t* Ks, const bf16x8* qr, const f32x16& negm, int r32, int hi) {
;   p0 = negm; p1 = negm;
; #pragma unroll
;   for (int d0 = 0; d0 < 6; ++d0) { int cb = (d0 * 16 + hi * 8) * 2;
;     bf16x8 b0 = *reinterpret_cast<const bf16x8*>((const char*)Ks + KSWZ(r32, cb));
;     bf16x8 b1 = *reinterpret_cast<const bf16x8*>((const char*)Ks + KSWZ(32 + r32, cb));
;     p0 = __builtin_amdgcn_mfma_f32_32x32x16_bf16(b0, qr[d0], p0, 0, 0, 0);
;     p1 = __builtin_amdgcn_mfma_f32_32x32x16_bf16(b1, qr[d0], p1, 0, 0, 0); }
; }
.Lat_rr_12:
	s_waitcnt lgkmcnt(0)
	s_barrier
	ds_read_b128 v[198:201], v142 offset:0
	ds_read_b128 v[202:205], v142 offset:8192
	ds_read_b128 v[206:209], v143 offset:0
	ds_read_b128 v[210:213], v143 offset:8192
	s_add_i32 m0, s6, 49152
	s_mov_b64 exec, s[20:21]
	global_load_lds_dwordx4 v146, s[14:15]
	s_add_i32 m0, s6, 50176
	s_mov_b64 exec, s[22:23]
	global_load_lds_dwordx4 v147, s[14:15]
	s_add_i32 m0, s7, 16384
	s_mov_b64 exec, -1
	global_load_lds_dwordx4 v149, s[14:15]
	v_add_u32_e32 v146, v146, v148
	v_add_u32_e32 v147, v147, v181
	v_add_u32_e32 v149, 0x38000, v149
	v_mfma_f32_32x32x16_bf16 v[34:49], v[182:185], v[114:117], v[98:113]
	ds_read_b128 v[182:185], v144 offset:0
	v_exp_f32_e32 v82, v82
	v_exp_f32_e32 v83, v83
	v_exp_f32_e32 v84, v84
	v_exp_f32_e32 v85, v85
	v_exp_f32_e32 v86, v86
	v_mfma_f32_32x32x16_bf16 v[50:65], v[186:189], v[114:117], v[98:113]
	ds_read_b128 v[186:189], v144 offset:8192
	v_exp_f32_e32 v87, v87
	v_exp_f32_e32 v88, v88
	v_exp_f32_e32 v89, v89
	v_exp_f32_e32 v90, v90
	v_exp_f32_e32 v91, v91
	v_mfma_f32_32x32x16_bf16 v[34:49], v[190:193], v[118:121], v[34:49]
	ds_read_b128 v[190:193], v145 offset:0
	v_exp_f32_e32 v92, v92
	v_exp_f32_e32 v93, v93
	v_exp_f32_e32 v94, v94
	v_exp_f32_e32 v95, v95
	v_exp_f32_e32 v96, v96
	v_mfma_f32_32x32x16_bf16 v[50:65], v[194:197], v[118:121], v[50:65]
	ds_read_b128 v[194:197], v145 offset:8192
	v_exp_f32_e32 v97, v97
	v_cvt_pk_bf16_f32 v158, v66, v67
	v_cvt_pk_bf16_f32 v159, v68, v69
	v_cvt_pk_bf16_f32 v160, v70, v71
	v_cvt_pk_bf16_f32 v161, v72, v73
	s_waitcnt lgkmcnt(7)
	v_mfma_f32_32x32x16_bf16 v[34:49], v[198:201], v[122:125], v[34:49]
	ds_read_b64_tr_b16 v[198:199], v150 offset:57344
	ds_read_b64_tr_b16 v[200:201], v150 offset:59392
	v_cvt_pk_bf16_f32 v162, v74, v75
	v_cvt_pk_bf16_f32 v163, v76, v77
	v_cvt_pk_bf16_f32 v164, v78, v79
	v_cvt_pk_bf16_f32 v165, v80, v81
	v_permlane32_swap_b32_e32 v158, v160
	s_waitcnt lgkmcnt(8)
	v_mfma_f32_32x32x16_bf16 v[50:65], v[202:205], v[122:125], v[50:65]
	ds_read_b64_tr_b16 v[202:203], v150 offset:57856
	ds_read_b64_tr_b16 v[204:205], v150 offset:59904
	v_permlane32_swap_b32_e32 v159, v161
	v_permlane32_swap_b32_e32 v162, v164
	v_permlane32_swap_b32_e32 v163, v165
	v_add_f32_e32 v214, v214, v82
	v_add_f32_e32 v215, v215, v83
	s_waitcnt lgkmcnt(9)
	v_mfma_f32_32x32x16_bf16 v[34:49], v[206:209], v[126:129], v[34:49]
	ds_read_b64_tr_b16 v[206:207], v150 offset:61440
	ds_read_b64_tr_b16 v[208:209], v150 offset:63488
	v_add_f32_e32 v216, v216, v84
	v_add_f32_e32 v217, v217, v85
	v_add_f32_e32 v214, v214, v86
	v_add_f32_e32 v215, v215, v87
	v_add_f32_e32 v216, v216, v88
	s_waitcnt lgkmcnt(10)
	v_mfma_f32_32x32x16_bf16 v[50:65], v[210:213], v[126:129], v[50:65]
	ds_read_b64_tr_b16 v[210:211], v150 offset:61952
	ds_read_b64_tr_b16 v[212:213], v150 offset:64000
	v_add_f32_e32 v217, v217, v89
	v_add_f32_e32 v214, v214, v90
	v_add_f32_e32 v215, v215, v91
	v_add_f32_e32 v216, v216, v92
	v_add_f32_e32 v217, v217, v93
	s_waitcnt lgkmcnt(11)
	v_mfma_f32_32x32x16_bf16 v[34:49], v[182:185], v[130:133], v[34:49]
	ds_read_b64_tr_b16 v[182:183], v150 offset:49152
	ds_read_b64_tr_b16 v[184:185], v150 offset:51200
	v_add_f32_e32 v214, v214, v94
	v_add_f32_e32 v215, v215, v95
	v_add_f32_e32 v216, v216, v96
	v_add_f32_e32 v217, v217, v97
	v_add_f32_e32 v214, v214, v215
	s_waitcnt lgkmcnt(12)
	v_mfma_f32_32x32x16_bf16 v[50:65], v[186:189], v[130:133], v[50:65]
	ds_read_b64_tr_b16 v[186:187], v150 offset:49664
	ds_read_b64_tr_b16 v[188:189], v150 offset:51712
	v_add_f32_e32 v216, v216, v217
	v_add_f32_e32 v214, v214, v216
	v_add_f32_e32 v174, v174, v214
	v_cvt_pk_bf16_f32 v166, v82, v83
	v_cvt_pk_bf16_f32 v167, v84, v85
	s_waitcnt lgkmcnt(13)
	v_mfma_f32_32x32x16_bf16 v[34:49], v[190:193], v[134:137], v[34:49]
	ds_read_b64_tr_b16 v[190:191], v150 offset:53248
	ds_read_b64_tr_b16 v[192:193], v150 offset:55296
	v_cvt_pk_bf16_f32 v168, v86, v87
	v_cvt_pk_bf16_f32 v169, v88, v89
	v_cvt_pk_bf16_f32 v170, v90, v91
	v_cvt_pk_bf16_f32 v171, v92, v93
	v_cvt_pk_bf16_f32 v172, v94, v95
	s_waitcnt lgkmcnt(14)
	v_mfma_f32_32x32x16_bf16 v[50:65], v[194:197], v[134:137], v[50:65]
	ds_read_b64_tr_b16 v[194:195], v150 offset:53760
	ds_read_b64_tr_b16 v[196:197], v150 offset:55808
	v_cvt_pk_bf16_f32 v173, v96, v97
	v_permlane32_swap_b32_e32 v166, v168
	v_permlane32_swap_b32_e32 v167, v169
	v_permlane32_swap_b32_e32 v170, v172
	v_permlane32_swap_b32_e32 v171, v173
	s_waitcnt lgkmcnt(6)
	v_mfma_f32_32x32x16_bf16 v[2:17], v[158:161], v[182:185], v[2:17]
	ds_read_b128 v[182:185], v140 offset:16384
	v_max3_f32 v177, v34, v35, v36
	v_max3_f32 v178, v37, v38, v39
	v_max3_f32 v177, v177, v40, v41
	s_waitcnt lgkmcnt(5)
	v_mfma_f32_32x32x16_bf16 v[18:33], v[158:161], v[186:189], v[18:33]
	ds_read_b128 v[186:189], v140 offset:24576
	v_max3_f32 v178, v178, v42, v43
	v_max3_f32 v177, v177, v44, v45
	v_max3_f32 v178, v178, v46, v47
	v_max3_f32 v177, v177, v48, v49
	v_max3_f32 v178, v178, v50, v51
	v_max3_f32 v177, v177, v52, v53
	s_waitcnt lgkmcnt(4)
	v_mfma_f32_32x32x16_bf16 v[2:17], v[162:165], v[190:193], v[2:17]
	ds_read_b128 v[190:193], v141 offset:16384
	v_max3_f32 v178, v178, v54, v55
	v_max3_f32 v177, v177, v56, v57
	v_max3_f32 v178, v178, v58, v59
	v_max3_f32 v177, v177, v60, v61
	v_max3_f32 v178, v178, v62, v63
	v_max3_f32 v177, v177, v64, v65
	s_waitcnt lgkmcnt(3)
	v_mfma_f32_32x32x16_bf16 v[18:33], v[162:165], v[194:197], v[18:33]
	ds_read_b128 v[194:197], v141 offset:24576
	v_max_f32_e32 v177, v177, v178
	v_mov_b32_e32 v178, v177
	s_nop 1
	v_permlane32_swap_b32_e32 v177, v178
	v_max_f32_e32 v177, v177, v178
	v_cmp_ge_f32_e32 vcc, 0x4138aa3b, v177
	s_cmp_eq_u64 vcc, exec
	s_cbranch_scc0 .Lat_rare1_14

; __device__ __forceinline__ void finishSM(f32x16& p0, f32x16& p1, float alpha, float& l_reg, bf16x8& pa0, bf16x8& pa1, bf16x8& pa2, bf16x8& pa3) {
; #pragma unroll
;   for (int r = 0; r < 16; ++r) p1[r] = __builtin_amdgcn_exp2f(p1[r]);
;   float ps = 0;
; #pragma unroll
;   for (int r = 0; r < 16; ++r) ps += p0[r];
; #pragma unroll
;   for (int r = 0; r < 16; ++r) ps += p1[r];
;   { auto rr = __builtin_amdgcn_permlane32_swap(__float_as_uint(ps), __float_as_uint(ps), false, false);
;     ps = __uint_as_float(rr[0]) + __uint_as_float(rr[1]); }
;   l_reg = l_reg * alpha + ps;
;     ...
;   PK4(p0, 0, pa0); PK4(p0, 8, pa1); PK4(p1, 0, pa2); PK4(p1, 8, pa3);
;     ...
; }
; __device__ __forceinline__ void qkt(f32x16& p0, f32x16& p1, const bf16_t* Ks, const bf16x8* qr, const f32x16& negm, int r32, int hi) {
;   p0 = negm; p1 = negm;
; #pragma unroll
;   for (int d0 = 0; d0 < 6; ++d0) { int cb = (d0 * 16 + hi * 8) * 2;
;     bf16x8 b0 = *reinterpret_cast<const bf16x8*>((const char*)Ks + KSWZ(r32, cb));
;     bf16x8 b1 = *reinterpret_cast<const bf16x8*>((const char*)Ks + KSWZ(32 + r32, cb));
;     p0 = __builtin_amdgcn_mfma_f32_32x32x16_bf16(b0, qr[d0], p0, 0, 0, 0);
;     p1 = __builtin_amdgcn_mfma_f32_32x32x16_bf16(b1, qr[d0], p1, 0, 0, 0); }
; }
; __device__ __forceinline__ int v_st(int k, int c) { const int kk = (k & ~0xC) | ((k & 4) << 1) | ((k & 8) >> 1); return ((kk >> 3) * 4 + (c >> 5)) * 512 + ((kk & 7) * 32 + (c & 31)) * 2; }
; __device__ __forceinline__ int v_rd_base(int lane) { return ((lane & 3) << 3) | (((lane >> 2) & 3) << 6) | (((lane >> 4) & 1) << 5) | (((lane >> 5) & 1) << 8); }
; template <int OFF> __device__ __forceinline__ s16x4 tr_read(int vb) {
;   s16x4 r; asm volatile("ds_read_b64_tr_b16 %0, %1 offset:%2" : "=&v"(r) : "v"(vb), "i"(OFF) : "memory"); return r;
; }
; __device__ __forceinline__ void attn_item(const bf16_t* __restrict__ Qb, const bf16_t* __restrict__ Kn, const bf16_t* __restrict__ Kr, const bf16_t* __restrict__ Vh,
;                                           const float* __restrict__ csq, bf16_t* __restrict__ Ob, int seq, char* lds) {
;     ...
;   for (int j = 1; j + 1 < NT; j += 2) {
;     STEP(pB0, pB1, alB, pA0, pA1, alA, j, true);
;     STEP(pA0, pA1, alA, pB0, pB1, alB, j + 1, true);
;   }
;   STEP(pB0, pB1, alB, pA0, pA1, alA, NT - 1, false);
.Lat_rr_16:
	s_waitcnt lgkmcnt(0)
	s_barrier
	s_add_i32 s8, s8, 1
	s_cmp_lt_u32 s8, 31
	s_cbranch_scc1 .Lat_loop
	ds_read_b128 v[198:201], v142 offset:16384
	ds_read_b128 v[202:205], v142 offset:24576
	ds_read_b128 v[206:209], v143 offset:16384
	ds_read_b128 v[210:213], v143 offset:24576
	s_add_i32 m0, s7, 32768
	s_mov_b64 exec, -1
	global_load_lds_dwordx4 v149, s[14:15]
	v_add_u32_e32 v149, 0x38000, v149
	v_mfma_f32_32x32x16_bf16 v[66:81], v[182:185], v[114:117], v[98:113]
	ds_read_b128 v[182:185], v144 offset:16384
	v_exp_f32_e32 v50, v50
	v_exp_f32_e32 v51, v51
	v_exp_f32_e32 v52, v52
	v_exp_f32_e32 v53, v53
	v_exp_f32_e32 v54, v54
	v_mfma_f32_32x32x16_bf16 v[82:97], v[186:189], v[114:117], v[98:113]
	ds_read_b128 v[186:189], v144 offset:24576
	v_exp_f32_e32 v55, v55
	v_exp_f32_e32 v56, v56
	v_exp_f32_e32 v57, v57
	v_exp_f32_e32 v58, v58
	v_exp_f32_e32 v59, v59
	v_mfma_f32_32x32x16_bf16 v[66:81], v[190:193], v[118:121], v[66:81]
	ds_read_b128 v[190:193], v145 offset:16384
	v_exp_f32_e32 v60, v60
	v_exp_f32_e32 v61, v61
	v_exp_f32_e32 v62, v62
	v_exp_f32_e32 v63, v63
	v_exp_f32_e32 v64, v64
	v_mfma_f32_32x32x16_bf16 v[82:97], v[194:197], v[118:121], v[82:97]
	ds_read_b128 v[194:197], v145 offset:24576
	v_exp_f32_e32 v65, v65
	v_cvt_pk_bf16_f32 v158, v34, v35
	v_cvt_pk_bf16_f32 v159, v36, v37
	v_cvt_pk_bf16_f32 v160, v38, v39
	v_cvt_pk_bf16_f32 v161, v40, v41
	s_waitcnt lgkmcnt(7)
	v_mfma_f32_32x32x16_bf16 v[66:81], v[198:201], v[122:125], v[66:81]
	ds_read_b64_tr_b16 v[198:199], v150 offset:8192
	ds_read_b64_tr_b16 v[200:201], v150 offset:10240
	v_cvt_pk_bf16_f32 v162, v42, v43
	v_cvt_pk_bf16_f32 v163, v44, v45
	v_cvt_pk_bf16_f32 v164, v46, v47
	v_cvt_pk_bf16_f32 v165, v48, v49
	v_permlane32_swap_b32_e32 v158, v160
	s_waitcnt lgkmcnt(8)
	v_mfma_f32_32x32x16_bf16 v[82:97], v[202:205], v[122:125], v[82:97]
	ds_read_b64_tr_b16 v[202:203], v150 offset:8704
	ds_read_b64_tr_b16 v[204:205], v150 offset:10752
	v_permlane32_swap_b32_e32 v159, v161
	v_permlane32_swap_b32_e32 v162, v164
	v_permlane32_swap_b32_e32 v163, v165
	v_add_f32_e32 v214, v214, v50
	v_add_f32_e32 v215, v215, v51
	s_waitcnt lgkmcnt(9)
	v_mfma_f32_32x32x16_bf16 v[66:81], v[206:209], v[126:129], v[66:81]
	ds_read_b64_tr_b16 v[206:207], v150 offset:12288
	ds_read_b64_tr_b16 v[208:209], v150 offset:14336
	v_add_f32_e32 v216, v216, v52
	v_add_f32_e32 v217, v217, v53
	v_add_f32_e32 v214, v214, v54
	v_add_f32_e32 v215, v215, v55
	v_add_f32_e32 v216, v216, v56
	s_waitcnt lgkmcnt(10)
	v_mfma_f32_32x32x16_bf16 v[82:97], v[210:213], v[126:129], v[82:97]
	ds_read_b64_tr_b16 v[210:211], v150 offset:12800
	ds_read_b64_tr_b16 v[212:213], v150 offset:14848
	v_add_f32_e32 v217, v217, v57
	v_add_f32_e32 v214, v214, v58
	v_add_f32_e32 v215, v215, v59
	v_add_f32_e32 v216, v216, v60
	v_add_f32_e32 v217, v217, v61
	s_waitcnt lgkmcnt(11)
	v_mfma_f32_32x32x16_bf16 v[66:81], v[182:185], v[130:133], v[66:81]
	ds_read_b64_tr_b16 v[182:183], v150 offset:0
	ds_read_b64_tr_b16 v[184:185], v150 offset:2048
	v_add_f32_e32 v214, v214, v62
	v_add_f32_e32 v215, v215, v63
	v_add_f32_e32 v216, v216, v64
	v_add_f32_e32 v217, v217, v65
	v_add_f32_e32 v214, v214, v215
	s_waitcnt lgkmcnt(12)
	v_mfma_f32_32x32x16_bf16 v[82:97], v[186:189], v[130:133], v[82:97]
	ds_read_b64_tr_b16 v[186:187], v150 offset:512
	ds_read_b64_tr_b16 v[188:189], v150 offset:2560
	v_add_f32_e32 v216, v216, v217
	v_add_f32_e32 v214, v214, v216
	v_add_f32_e32 v174, v174, v214
	v_cvt_pk_bf16_f32 v166, v50, v51
	v_cvt_pk_bf16_f32 v167, v52, v53
	s_waitcnt lgkmcnt(13)
	v_mfma_f32_32x32x16_bf16 v[66:81], v[190:193], v[134:137], v[66:81]
	ds_read_b64_tr_b16 v[190:191], v150 offset:4096
	ds_read_b64_tr_b16 v[192:193], v150 offset:6144
	v_cvt_pk_bf16_f32 v168, v54, v55
	v_cvt_pk_bf16_f32 v169, v56, v57
	v_cvt_pk_bf16_f32 v170, v58, v59
	v_cvt_pk_bf16_f32 v171, v60, v61
	v_cvt_pk_bf16_f32 v172, v62, v63
	s_waitcnt lgkmcnt(14)
	v_mfma_f32_32x32x16_bf16 v[82:97], v[194:197], v[134:137], v[82:97]
	ds_read_b64_tr_b16 v[194:195], v150 offset:4608
	ds_read_b64_tr_b16 v[196:197], v150 offset:6656
	v_cvt_pk_bf16_f32 v173, v64, v65
	v_permlane32_swap_b32_e32 v166, v168
	v_permlane32_swap_b32_e32 v167, v169
	v_permlane32_swap_b32_e32 v170, v172
	v_permlane32_swap_b32_e32 v171, v173
	s_waitcnt lgkmcnt(6)
	v_mfma_f32_32x32x16_bf16 v[2:17], v[158:161], v[182:185], v[2:17]
	ds_read_b128 v[182:185], v140 offset:32768
	v_max3_f32 v177, v66, v67, v68
	v_max3_f32 v178, v69, v70, v71
	v_max3_f32 v177, v177, v72, v73
	s_waitcnt lgkmcnt(5)
	v_mfma_f32_32x32x16_bf16 v[18:33], v[158:161], v[186:189], v[18:33]
	ds_read_b128 v[186:189], v140 offset:40960
	v_max3_f32 v178, v178, v74, v75
	v_max3_f32 v177, v177, v76, v77
	v_max3_f32 v178, v178, v78, v79
	v_max3_f32 v177, v177, v80, v81
	v_max3_f32 v178, v178, v82, v83
	v_max3_f32 v177, v177, v84, v85
	s_waitcnt lgkmcnt(4)
	v_mfma_f32_32x32x16_bf16 v[2:17], v[162:165], v[190:193], v[2:17]
	ds_read_b128 v[190:193], v141 offset:32768
	v_max3_f32 v178, v178, v86, v87
	v_max3_f32 v177, v177, v88, v89
	v_max3_f32 v178, v178, v90, v91
	v_max3_f32 v177, v177, v92, v93
	v_max3_f32 v178, v178, v94, v95
	v_max3_f32 v177, v177, v96, v97
	s_waitcnt lgkmcnt(3)
	v_mfma_f32_32x32x16_bf16 v[18:33], v[162:165], v[194:197], v[18:33]
	ds_read_b128 v[194:197], v141 offset:40960
	v_max_f32_e32 v177, v177, v178
	v_mov_b32_e32 v178, v177
	s_nop 1
	v_permlane32_swap_b32_e32 v177, v178
	v_max_f32_e32 v177, v177, v178
	v_cmp_ge_f32_e32 vcc, 0x4138aa3b, v177
	s_cmp_eq_u64 vcc, exec
	s_cbranch_scc0 .Lat_rare1_18

; template <bool FIRST> __device__ __forceinline__ void partialSM(f32x16& p0, f32x16& p1, float& mhat, f32x16& negm, float& alpha) {
;     ...
;   if (!FIRST && __builtin_expect(__all(pmax <= THRL), 1)) { alpha = 1.f; }
;   else { const float d = FIRST ? pmax : fmaxf(pmax, 0.f); mhat += d; alpha = FIRST ? 1.f : __builtin_amdgcn_exp2f(-d);
; #pragma unroll
;     for (int r = 0; r < 16; ++r) { p0[r] -= d; p1[r] -= d; }
; #pragma unroll
;     for (int r = 0; r < 16; ++r) negm[r] = -mhat; }
.Lat_rare1_2:
	s_movk_i32 s10, 0
	s_branch .Lat_rareI_66
.Lat_rare1_6:
	s_movk_i32 s10, 1
	s_branch .Lat_rareI_34
.Lat_rare1_10:
	s_movk_i32 s10, 2
	s_branch .Lat_rareI_66
.Lat_rare1_14:
	s_movk_i32 s10, 3
	s_branch .Lat_rareI_34
.Lat_rare1_18:
	s_movk_i32 s10, 4
	s_branch .Lat_rareI_66
.Lat_rare1_22:
	s_movk_i32 s10, 5
	s_branch .Lat_rareI_34
.Lat_rare1_26:
	s_movk_i32 s10, 6
	s_branch .Lat_rareI_66

; template <bool FIRST> __device__ __forceinline__ void partialSM(f32x16& p0, f32x16& p1, float& mhat, f32x16& negm, float& alpha) {
;   float pa = fmaxf(fmaxf(p0[0], p0[1]), p1[0]), pb = fmaxf(fmaxf(p0[2], p0[3]), p1[1]); pa = fmaxf(fmaxf(pa, p1[2]), p1[3]);
; #pragma unroll
;   for (int r = 4; r < 16; r += 4) { pa = fmaxf(fmaxf(pa, p0[r]), p0[r + 1]); pb = fmaxf(fmaxf(pb, p0[r + 2]), p0[r + 3]); pa = fmaxf(fmaxf(pa, p1[r]), p1[r + 1]); pb = fmaxf(fmaxf(pb, p1[r + 2]), p1[r + 3]); }
;   float pmax = fmaxf(pa, pb);
;   { auto rr = __builtin_amdgcn_permlane32_swap(__float_as_uint(pmax), __float_as_uint(pmax), false, false);
;     pmax = fmaxf(__uint_as_float(rr[0]), __uint_as_float(rr[1])); }
;   if (!FIRST && __builtin_expect(__all(pmax <= THRL), 1)) { alpha = 1.f; }
;   else { const float d = FIRST ? pmax : fmaxf(pmax, 0.f); mhat += d; alpha = FIRST ? 1.f : __builtin_amdgcn_exp2f(-d);
; #pragma unroll
;     for (int r = 0; r < 16; ++r) { p0[r] -= d; p1[r] -= d; }
; #pragma unroll
;     for (int r = 0; r < 16; ++r) negm[r] = -mhat; }
; #pragma unroll
;   for (int r = 0; r < 16; ++r) p0[r] = __builtin_amdgcn_exp2f(p0[r]);
; }
.Lat_rare2_30:
	s_movk_i32 s10, 7
	s_branch .Lat_rareII
.Lat_rareI_34:
	v_max_f32_e32 v177, 0, v177
	v_exp_f32_e64 v178, -v177
	v_add_f32_e32 v151, v151, v177
	v_sub_f32_e32 v34, v34, v177
	v_sub_f32_e32 v35, v35, v177
	v_sub_f32_e32 v36, v36, v177
	v_sub_f32_e32 v37, v37, v177
	v_sub_f32_e32 v38, v38, v177
	v_sub_f32_e32 v39, v39, v177
	v_sub_f32_e32 v40, v40, v177
	v_sub_f32_e32 v41, v41, v177
	v_sub_f32_e32 v42, v42, v177
	v_sub_f32_e32 v43, v43, v177
	v_sub_f32_e32 v44, v44, v177
	v_sub_f32_e32 v45, v45, v177
	v_sub_f32_e32 v46, v46, v177
	v_sub_f32_e32 v47, v47, v177
	v_sub_f32_e32 v48, v48, v177
	v_sub_f32_e32 v49, v49, v177
	v_sub_f32_e32 v50, v50, v177
	v_sub_f32_e32 v51, v51, v177
	v_sub_f32_e32 v52, v52, v177
	v_sub_f32_e32 v53, v53, v177
	v_sub_f32_e32 v54, v54, v177
	v_sub_f32_e32 v55, v55, v177
	v_sub_f32_e32 v56, v56, v177
	v_sub_f32_e32 v57, v57, v177
	v_sub_f32_e32 v58, v58, v177
	v_sub_f32_e32 v59, v59, v177
	v_sub_f32_e32 v60, v60, v177
	v_sub_f32_e32 v61, v61, v177
	v_sub_f32_e32 v62, v62, v177
	v_sub_f32_e32 v63, v63, v177
	v_sub_f32_e32 v64, v64, v177
	v_sub_f32_e32 v65, v65, v177
	v_xor_b32_e32 v98, 0x80000000, v151
	v_mov_b32_e32 v99, v98
	v_mov_b32_e32 v100, v98
	v_mov_b32_e32 v101, v98
	v_mov_b32_e32 v102, v98
	v_mov_b32_e32 v103, v98
	v_mov_b32_e32 v104, v98
	v_mov_b32_e32 v105, v98
	v_mov_b32_e32 v106, v98
	v_mov_b32_e32 v107, v98
	v_mov_b32_e32 v108, v98
	v_mov_b32_e32 v109, v98
	v_mov_b32_e32 v110, v98
	v_mov_b32_e32 v111, v98
	v_mov_b32_e32 v112, v98
	v_mov_b32_e32 v113, v98
	v_mul_f32_e32 v174, v174, v178
	s_mov_b32 exec_hi, 0
	ds_write_b32 v175, v178 offset:128
	s_mov_b64 exec, -1
	s_mov_b32 s9, 1
	s_nop 3
	s_cmp_eq_u32 s10, 1
	s_cbranch_scc1 .Lat_ri_5
	s_cmp_eq_u32 s10, 3
	s_cbranch_scc1 .Lat_ri_13
	s_cmp_eq_u32 s10, 5
	s_cbranch_scc1 .Lat_ri_21
	s_endpgm
.Lat_rareI_66:
	v_max_f32_e32 v177, 0, v177
	v_exp_f32_e64 v178, -v177
	v_add_f32_e32 v151, v151, v177
	v_sub_f32_e32 v66, v66, v177
	v_sub_f32_e32 v67, v67, v177
	v_sub_f32_e32 v68, v68, v177
	v_sub_f32_e32 v69, v69, v177
	v_sub_f32_e32 v70, v70, v177
	v_sub_f32_e32 v71, v71, v177
	v_sub_f32_e32 v72, v72, v177
	v_sub_f32_e32 v73, v73, v177
	v_sub_f32_e32 v74, v74, v177
	v_sub_f32_e32 v75, v75, v177
	v_sub_f32_e32 v76, v76, v177
	v_sub_f32_e32 v77, v77, v177
	v_sub_f32_e32 v78, v78, v177
	v_sub_f32_e32 v79, v79, v177
	v_sub_f32_e32 v80, v80, v177
	v_sub_f32_e32 v81, v81, v177
	v_sub_f32_e32 v82, v82, v177
	v_sub_f32_e32 v83, v83, v177
	v_sub_f32_e32 v84, v84, v177
	v_sub_f32_e32 v85, v85, v177
	v_sub_f32_e32 v86, v86, v177
	v_sub_f32_e32 v87, v87, v177
	v_sub_f32_e32 v88, v88, v177
	v_sub_f32_e32 v89, v89, v177
	v_sub_f32_e32 v90, v90, v177
	v_sub_f32_e32 v91, v91, v177
	v_sub_f32_e32 v92, v92, v177
	v_sub_f32_e32 v93, v93, v177
	v_sub_f32_e32 v94, v94, v177
	v_sub_f32_e32 v95, v95, v177
	v_sub_f32_e32 v96, v96, v177
	v_sub_f32_e32 v97, v97, v177
	v_xor_b32_e32 v98, 0x80000000, v151
	v_mov_b32_e32 v99, v98
	v_mov_b32_e32 v100, v98
	v_mov_b32_e32 v101, v98
	v_mov_b32_e32 v102, v98
	v_mov_b32_e32 v103, v98
	v_mov_b32_e32 v104, v98
	v_mov_b32_e32 v105, v98
	v_mov_b32_e32 v106, v98
	v_mov_b32_e32 v107, v98
	v_mov_b32_e32 v108, v98
	v_mov_b32_e32 v109, v98
	v_mov_b32_e32 v110, v98
	v_mov_b32_e32 v111, v98
	v_mov_b32_e32 v112, v98
	v_mov_b32_e32 v113, v98
	v_mul_f32_e32 v174, v174, v178
	s_mov_b32 exec_hi, 0
	ds_write_b32 v175, v178 offset:128
	s_mov_b64 exec, -1
	s_mov_b32 s9, 1
	s_nop 3
	s_cmp_eq_u32 s10, 0
	s_cbranch_scc1 .Lat_ri_1
	s_cmp_eq_u32 s10, 2
	s_cbranch_scc1 .Lat_ri_9
	s_cmp_eq_u32 s10, 4
	s_cbranch_scc1 .Lat_ri_17
	s_cmp_eq_u32 s10, 6
	s_cbranch_scc1 .Lat_ri_25
	s_endpgm
.Lat_rareII:
	s_nop 15
	s_waitcnt lgkmcnt(0)
	ds_read_b128 v[198:201], v176 offset:128
	ds_read_b128 v[202:205], v176 offset:160
	ds_read_b128 v[206:209], v176 offset:192
	ds_read_b128 v[210:213], v176 offset:224
	s_waitcnt lgkmcnt(0)
	v_mul_f32_e32 v2, v2, v198
	v_mul_f32_e32 v3, v3, v199
	v_mul_f32_e32 v4, v4, v200
	v_mul_f32_e32 v5, v5, v201
	v_mul_f32_e32 v6, v6, v202
	v_mul_f32_e32 v7, v7, v203
	v_mul_f32_e32 v8, v8, v204
	v_mul_f32_e32 v9, v9, v205
	v_mul_f32_e32 v10, v10, v206
	v_mul_f32_e32 v11, v11, v207
	v_mul_f32_e32 v12, v12, v208
	v_mul_f32_e32 v13, v13, v209
	v_mul_f32_e32 v14, v14, v210
	v_mul_f32_e32 v15, v15, v211
	v_mul_f32_e32 v16, v16, v212
	v_mul_f32_e32 v17, v17, v213
	v_mul_f32_e32 v18, v18, v198
	v_mul_f32_e32 v19, v19, v199
	v_mul_f32_e32 v20, v20, v200
	v_mul_f32_e32 v21, v21, v201
	v_mul_f32_e32 v22, v22, v202
	v_mul_f32_e32 v23, v23, v203
	v_mul_f32_e32 v24, v24, v204
	v_mul_f32_e32 v25, v25, v205
	v_mul_f32_e32 v26, v26, v206
	v_mul_f32_e32 v27, v27, v207
	v_mul_f32_e32 v28, v28, v208
	v_mul_f32_e32 v29, v29, v209
	v_mul_f32_e32 v30, v30, v210
	v_mul_f32_e32 v31, v31, v211
	v_mul_f32_e32 v32, v32, v212
	v_mul_f32_e32 v33, v33, v213
	s_mov_b32 s9, 0
	s_nop 3
	s_cmp_eq_u32 s10, 0
	s_cbranch_scc1 .Lat_rr_4
	s_cmp_eq_u32 s10, 1
	s_cbranch_scc1 .Lat_rr_8
	s_cmp_eq_u32 s10, 2
	s_cbranch_scc1 .Lat_rr_12
	s_cmp_eq_u32 s10, 3
	s_cbranch_scc1 .Lat_rr_16
	s_cmp_eq_u32 s10, 4
	s_cbranch_scc1 .Lat_rr_20
	s_cmp_eq_u32 s10, 5
	s_cbranch_scc1 .Lat_rr_24
	s_cmp_eq_u32 s10, 6
	s_cbranch_scc1 .Lat_rr_28
	s_cmp_eq_u32 s10, 7
	s_cbranch_scc1 .Lat_rr_31
	s_endpgm
